# weight conversion: L1 loop - prefetched tile waited only before it becomes current; L0 loop - 8 strided loads issued together
# speedup vs baseline: 1.0172x; 1.0087x over previous
.LBB0_53:
	s_or_b64 exec, exec, s[4:5]
	s_waitcnt lgkmcnt(0)
	s_add_u32 s26, s2, 0x2a80000
	s_addc_u32 s27, s3, 0
	v_mov_b32_e32 v6, v1
	v_mov_b32_e32 v7, v1
	s_add_u32 s28, s2, 0x2100000
	v_mov_b32_e32 v0, v1
	v_mov_b32_e32 v2, v1
	v_mov_b32_e32 v3, v1
	v_mov_b32_e32 v4, v1
	v_mov_b32_e32 v5, v1
	v_mov_b64_e32 v[22:23], v[6:7]
	s_addc_u32 s29, s3, 0
	s_mov_b32 s52, 0
	s_mov_b32 s53, 0x1600000
	s_movk_i32 s54, 0x1210
	s_movk_i32 s55, 0x104
	v_mov_b64_e32 v[20:21], v[4:5]
	v_mov_b64_e32 v[18:19], v[2:3]
	v_mov_b64_e32 v[16:17], v[0:1]
	s_waitcnt vmcnt(0)
	s_branch .LBB0_55

.LBB0_71:
	s_xor_b64 s[4:5], s[4:5], -1
	s_mul_i32 s60, s60, s59
	s_sub_i32 s42, s57, s60
	s_sext_i32_i16 s42, s42
	v_ashrrev_i32_e32 v0, 6, v6
	v_lshl_add_u32 v0, s42, 6, v0
	v_mov_b32_e32 v16, 0
	v_mov_b32_e32 v17, 0
	v_mov_b32_e32 v18, 0
	v_mov_b32_e32 v19, 0
	v_mov_b32_e32 v20, 0
	v_mov_b32_e32 v21, 0
	v_mov_b32_e32 v22, 0
	v_mov_b32_e32 v23, 0
	s_andn2_b64 s[4:5], exec, s[4:5]
	s_mov_b64 s[40:41], exec
	s_mov_b64 exec, s[4:5]
	s_cbranch_execz .Lcvt0_noload
	v_ashrrev_i32_e32 v5, 31, v0
	v_mul_lo_u32 v6, s38, v5
	v_mul_lo_u32 v7, s39, v0
	v_mad_u64_u32 v[4:5], s[42:43], s38, v0, 0
	v_add3_u32 v5, v5, v6, v7
	v_lshl_add_u64 v[4:5], v[4:5], 2, v[2:3]
	s_lshl_b64 s[42:43], s[38:39], 5
	global_load_dword v16, v[4:5], off
	v_lshl_add_u64 v[4:5], v[4:5], 0, s[42:43]
	global_load_dword v17, v[4:5], off
	v_lshl_add_u64 v[4:5], v[4:5], 0, s[42:43]
	global_load_dword v18, v[4:5], off
	v_lshl_add_u64 v[4:5], v[4:5], 0, s[42:43]
	global_load_dword v19, v[4:5], off
	v_lshl_add_u64 v[4:5], v[4:5], 0, s[42:43]
	global_load_dword v20, v[4:5], off
	v_lshl_add_u64 v[4:5], v[4:5], 0, s[42:43]
	global_load_dword v21, v[4:5], off
	v_lshl_add_u64 v[4:5], v[4:5], 0, s[42:43]
	global_load_dword v22, v[4:5], off
	v_lshl_add_u64 v[4:5], v[4:5], 0, s[42:43]
	global_load_dword v23, v[4:5], off
.Lcvt0_noload:
	s_mov_b64 exec, s[40:41]
	s_mov_b64 s[4:5], exec

.LBB0_88:
	s_lshr_b32 s4, s51, 6
	v_cvt_f32_u32_e32 v6, s4
	v_mov_b32_e32 v0, v178
	s_sub_i32 s39, 0, s4
	v_and_b32_e32 v2, 63, v0
	v_ashrrev_i32_e32 v3, 6, v0
	v_lshlrev_b32_e32 v2, 2, v2
	v_mul_lo_u32 v3, v3, s55
	v_ashrrev_i32_e32 v26, 3, v0
	v_lshlrev_b32_e32 v0, 3, v0
	v_add3_u32 v2, 0, v2, v3
	v_and_b32_e32 v27, 56, v0
	v_rcp_iflag_f32_e32 v28, v6
	ds_write_b32 v2, v8
	ds_write_b32 v2, v9 offset:2080
	ds_write_b32 v2, v10 offset:4160
	ds_write_b32 v2, v11 offset:6240
	ds_write_b32 v2, v12 offset:8320
	ds_write_b32 v2, v13 offset:10400
	ds_write_b32 v2, v14 offset:12480
	ds_write_b32 v2, v15 offset:14560
	v_lshlrev_b32_e32 v0, 2, v26
	v_mul_u32_u24_e32 v2, 0x104, v27
	v_add3_u32 v0, 0, v0, v2
	s_waitcnt lgkmcnt(0)
	s_barrier
	ds_read2_b32 v[2:3], v0 offset1:65
	ds_read2_b32 v[4:5], v0 offset0:130 offset1:195
	v_add_u32_e32 v0, 0x400, v0
	ds_read2_b32 v[6:7], v0 offset0:4 offset1:69
	ds_read2_b32 v[24:25], v0 offset0:134 offset1:199
	v_mul_f32_e32 v0, 0x4f7ffffe, v28
	v_cvt_u32_f32_e32 v0, v0
	s_abs_i32 s38, s50
	s_ashr_i32 s5, s50, 31
	s_waitcnt lgkmcnt(3)
	v_cvt_pk_bf16_f32 v2, v2, v3
	v_readfirstlane_b32 s40, v0
	s_mul_i32 s39, s39, s40
	s_mul_hi_u32 s39, s40, s39
	s_add_i32 s40, s40, s39
	s_mul_hi_u32 s39, s38, s40
	s_mul_i32 s40, s39, s4
	s_sub_i32 s38, s38, s40
	s_add_i32 s40, s39, 1
	s_sub_i32 s41, s38, s4
	s_cmp_ge_u32 s38, s4
	s_cselect_b32 s39, s40, s39
	s_cselect_b32 s38, s41, s38
	s_add_i32 s40, s39, 1
	s_cmp_ge_u32 s38, s4
	s_cselect_b32 s38, s40, s39
	s_xor_b32 s38, s38, s5
	s_sub_i32 s5, s38, s5
	v_lshl_add_u32 v0, s5, 6, v26
	s_waitcnt lgkmcnt(2)
	v_cvt_pk_bf16_f32 v3, v4, v5
	s_waitcnt lgkmcnt(1)
	v_cvt_pk_bf16_f32 v4, v6, v7
	v_mad_u64_u32 v[6:7], s[38:39], v0, s51, 0
	s_mul_i32 s4, s5, s4
	s_waitcnt lgkmcnt(0)
	v_cvt_pk_bf16_f32 v5, v24, v25
	v_ashrrev_i32_e32 v24, 31, v0
	v_mov_b32_e32 v0, v7
	s_sub_i32 s4, s50, s4
	v_mad_u64_u32 v[24:25], s[38:39], v24, s51, v[0:1]
	s_lshl_b32 s4, s4, 6
	v_mov_b32_e32 v7, v24
	v_lshl_add_u64 v[6:7], v[6:7], 1, s[24:25]
	s_ashr_i32 s5, s4, 31
	v_lshl_add_u64 v[6:7], s[4:5], 1, v[6:7]
	v_lshlrev_b32_e32 v0, 1, v27
	v_lshl_add_u64 v[6:7], v[6:7], 0, v[0:1]
	s_andn2_b64 vcc, exec, s[34:35]
	global_store_dwordx4 v[6:7], v[2:5], off
	s_barrier
	s_cbranch_vccnz .LBB0_54
	s_waitcnt vmcnt(1)
	v_mov_b64_e32 v[8:9], v[16:17]
	s_mov_b32 s50, s57
	s_mov_b32 s51, s58
	s_mov_b64 s[24:25], s[36:37]
	v_mov_b64_e32 v[10:11], v[18:19]
	v_mov_b64_e32 v[12:13], v[20:21]
	v_mov_b64_e32 v[14:15], v[22:23]
	s_mov_b32 s48, s56
	s_branch .LBB0_54

.LBB0_211:
	s_mul_i32 s39, s39, s38
	s_sub_i32 s28, s47, s39
	s_sext_i32_i16 s28, s28
	v_ashrrev_i32_e32 v1, 6, v1
	v_lshl_add_u32 v1, s28, 6, v1
	v_ashrrev_i32_e32 v4, 31, v1
	v_mul_lo_u32 v6, s26, v4
	v_mul_lo_u32 v7, s27, v1
	v_mad_u64_u32 v[4:5], s[28:29], s26, v1, 0
	v_add3_u32 v5, v5, v6, v7
	v_add_u32_e32 v6, 8, v1
	v_ashrrev_i32_e32 v7, 31, v6
	v_mul_lo_u32 v8, s26, v7
	v_mul_lo_u32 v9, s27, v6
	v_mad_u64_u32 v[6:7], s[28:29], s26, v6, 0
	v_add3_u32 v7, v7, v8, v9
	v_add_u32_e32 v8, 16, v1
	v_ashrrev_i32_e32 v9, 31, v8
	v_mul_lo_u32 v10, s26, v9
	v_mul_lo_u32 v11, s27, v8
	v_mad_u64_u32 v[8:9], s[28:29], s26, v8, 0
	v_add3_u32 v9, v9, v10, v11
	v_add_u32_e32 v10, 24, v1
	v_ashrrev_i32_e32 v11, 31, v10
	v_mul_lo_u32 v12, s26, v11
	v_mul_lo_u32 v13, s27, v10
	v_mad_u64_u32 v[10:11], s[28:29], s26, v10, 0
	v_add3_u32 v11, v11, v12, v13
	v_add_u32_e32 v12, 32, v1
	v_ashrrev_i32_e32 v13, 31, v12
	v_mul_lo_u32 v14, s26, v13
	v_mul_lo_u32 v15, s27, v12
	v_mad_u64_u32 v[12:13], s[28:29], s26, v12, 0
	v_add3_u32 v13, v13, v14, v15
	v_add_u32_e32 v14, 40, v1
	v_ashrrev_i32_e32 v15, 31, v14
	v_mul_lo_u32 v16, s26, v15
	v_mul_lo_u32 v17, s27, v14
	v_mad_u64_u32 v[14:15], s[28:29], s26, v14, 0
	v_add3_u32 v15, v15, v16, v17
	v_add_u32_e32 v16, 48, v1
	v_ashrrev_i32_e32 v17, 31, v16
	s_waitcnt vmcnt(3)
	v_mul_lo_u32 v18, s26, v17
	v_mul_lo_u32 v19, s27, v16
	v_mad_u64_u32 v[16:17], s[28:29], s26, v16, 0
	v_add_u32_e32 v1, 56, v1
	v_add3_u32 v17, v17, v18, v19
	v_ashrrev_i32_e32 v18, 31, v1
	v_mul_lo_u32 v20, s26, v18
	v_mul_lo_u32 v21, s27, v1
	v_mad_u64_u32 v[18:19], s[26:27], s26, v1, 0
	v_lshl_add_u64 v[4:5], v[4:5], 2, v[2:3]
	v_lshl_add_u64 v[6:7], v[6:7], 2, v[2:3]
	v_lshl_add_u64 v[8:9], v[8:9], 2, v[2:3]
	v_lshl_add_u64 v[10:11], v[10:11], 2, v[2:3]
	v_lshl_add_u64 v[12:13], v[12:13], 2, v[2:3]
	v_add3_u32 v19, v19, v20, v21
	v_lshl_add_u64 v[14:15], v[14:15], 2, v[2:3]
	v_lshl_add_u64 v[16:17], v[16:17], 2, v[2:3]
	v_lshl_add_u64 v[2:3], v[18:19], 2, v[2:3]
	global_load_dword v1, v[4:5], off
	s_nop 0
	global_load_dword v6, v[6:7], off
	s_nop 0
	global_load_dword v7, v[8:9], off
	s_nop 0
	global_load_dword v8, v[10:11], off
	global_load_dword v9, v[12:13], off
	s_nop 0
	global_load_dword v10, v[14:15], off
	global_load_dword v11, v[16:17], off
	global_load_dword v12, v[2:3], off
	s_waitcnt lgkmcnt(0)
	s_add_u32 s26, s2, 0x2900000
	s_addc_u32 s27, s3, 0
	s_add_u32 s28, s2, 0x2100000
	s_addc_u32 s29, s3, 0
	v_mov_b32_e32 v2, 0
	v_mov_b32_e32 v3, 0
	v_mov_b32_e32 v4, 0
	v_mov_b32_e32 v5, 0
	v_mov_b32_e32 v13, 0
	v_mov_b32_e32 v14, 0
	v_mov_b32_e32 v15, 0
	v_mov_b32_e32 v16, 0
	s_mov_b64 s[34:35], s[24:25]
	s_mov_b32 s51, s48
	s_mov_b32 s49, s47
	s_waitcnt vmcnt(0)
	s_branch .LBB0_214

.LBB0_213:
	v_mov_b32_e32 v17, v178
	s_movk_i32 s36, 0x104
	v_and_b32_e32 v18, 63, v17
	v_ashrrev_i32_e32 v19, 6, v17
	v_lshlrev_b32_e32 v18, 2, v18
	v_mul_lo_u32 v19, v19, s36
	v_add3_u32 v18, 0, v18, v19
	s_lshr_b32 s36, s48, 6
	ds_write_b32 v18, v1
	ds_write_b32 v18, v6 offset:2080
	ds_write_b32 v18, v7 offset:4160
	ds_write_b32 v18, v8 offset:6240
	ds_write_b32 v18, v9 offset:8320
	ds_write_b32 v18, v10 offset:10400
	ds_write_b32 v18, v11 offset:12480
	ds_write_b32 v18, v12 offset:14560
	v_cvt_f32_u32_e32 v10, s36
	s_sub_i32 s39, 0, s36
	s_abs_i32 s38, s47
	v_lshlrev_b32_e32 v6, 3, v17
	v_rcp_iflag_f32_e32 v12, v10
	s_ashr_i32 s37, s47, 31
	v_ashrrev_i32_e32 v1, 3, v17
	v_and_b32_e32 v17, 56, v6
	v_mul_f32_e32 v12, 0x4f7ffffe, v12
	v_cvt_u32_f32_e32 v12, v12
	v_lshlrev_b32_e32 v6, 2, v1
	v_mul_u32_u24_e32 v7, 0x104, v17
	v_add3_u32 v11, 0, v6, v7
	v_readfirstlane_b32 s40, v12
	s_mul_i32 s39, s39, s40
	s_mul_hi_u32 s39, s40, s39
	s_add_i32 s40, s40, s39
	s_mul_hi_u32 s39, s38, s40
	s_mul_i32 s40, s39, s36
	s_sub_i32 s38, s38, s40
	s_add_i32 s40, s39, 1
	s_sub_i32 s41, s38, s36
	s_cmp_ge_u32 s38, s36
	s_cselect_b32 s39, s40, s39
	s_cselect_b32 s38, s41, s38
	s_add_i32 s40, s39, 1
	s_waitcnt lgkmcnt(0)
	s_barrier
	ds_read2_b32 v[6:7], v11 offset1:65
	ds_read2_b32 v[8:9], v11 offset0:130 offset1:195
	v_add_u32_e32 v18, 0x400, v11
	s_cmp_ge_u32 s38, s36
	ds_read2_b32 v[10:11], v18 offset0:4 offset1:69
	ds_read2_b32 v[18:19], v18 offset0:134 offset1:199
	s_cselect_b32 s38, s40, s39
	s_xor_b32 s38, s38, s37
	s_sub_i32 s37, s38, s37
	v_lshl_add_u32 v1, s37, 6, v1
	s_waitcnt lgkmcnt(3)
	v_cvt_pk_bf16_f32 v6, v6, v7
	s_waitcnt lgkmcnt(2)
	v_cvt_pk_bf16_f32 v7, v8, v9
	s_waitcnt lgkmcnt(1)
	v_cvt_pk_bf16_f32 v8, v10, v11
	v_mad_u64_u32 v[10:11], s[38:39], v1, s48, 0
	s_mul_i32 s36, s37, s36
	s_waitcnt lgkmcnt(0)
	v_cvt_pk_bf16_f32 v9, v18, v19
	v_ashrrev_i32_e32 v18, 31, v1
	v_mov_b32_e32 v12, v11
	s_sub_i32 s36, s47, s36
	v_mad_u64_u32 v[18:19], s[38:39], v18, s48, v[12:13]
	s_lshl_b32 s36, s36, 6
	v_mov_b32_e32 v11, v18
	v_lshl_add_u64 v[10:11], v[10:11], 1, s[24:25]
	s_ashr_i32 s37, s36, 31
	v_lshl_add_u64 v[10:11], s[36:37], 1, v[10:11]
	v_lshlrev_b32_e32 v18, 1, v17
	v_mov_b32_e32 v19, v0
	v_lshl_add_u64 v[10:11], v[10:11], 0, v[18:19]
	global_store_dwordx4 v[10:11], v[6:9], off
	s_andn2_b64 vcc, exec, s[30:31]
	s_mov_b32 s47, s49
	s_mov_b32 s48, s51
	s_mov_b64 s[24:25], s[34:35]
	s_waitcnt vmcnt(1)
	v_mov_b32_e32 v1, v2
	v_mov_b32_e32 v6, v3
	v_mov_b32_e32 v7, v4
	v_mov_b32_e32 v8, v5
	v_mov_b32_e32 v9, v13
	v_mov_b32_e32 v10, v14
	v_mov_b32_e32 v11, v15
	v_mov_b32_e32 v12, v16
	s_barrier
	s_cbranch_vccz .LBB0_231

.LBB0_1205:
	s_ashr_i32 s21, s20, 31
	s_lshl_b64 s[26:27], s[20:21], 17
	s_add_u32 s26, s36, s26
	s_addc_u32 s27, s37, s27
	s_and_b64 s[6:7], s[6:7], exec
	s_cselect_b32 s7, s27, s31
	s_cselect_b32 s6, s26, s30
	s_add_i32 s23, 0, 0x10000
	v_add_u32_e32 v173, s23, v1
	ds_read_b128 v[2:5], v173
	ds_read_b128 v[6:9], v173 offset:1024
	ds_read_b128 v[10:13], v173 offset:2048
	ds_read_b128 v[14:17], v173 offset:3072
	s_add_u32 s46, s28, 0x40080
	s_addc_u32 s47, s29, 0
	s_add_i32 s50, s3, 0xc000
	v_lshl_add_u64 v[50:51], s[46:47], 0, v[138:139]
	s_mov_b32 m0, s50
	s_add_i32 s21, s3, 0xe000
	ds_read_b128 v[18:21], v172
	ds_read_b128 v[22:25], v172 offset:1024
	ds_read_b128 v[26:29], v172 offset:2048
	ds_read_b128 v[30:33], v172 offset:3072
	ds_read_b128 v[34:37], v172 offset:4096
	ds_read_b128 v[38:41], v172 offset:5120
	ds_read_b128 v[42:45], v172 offset:6144
	ds_read_b128 v[46:49], v172 offset:7168
	global_load_lds_dwordx4 v[50:51], off
	v_lshl_add_u64 v[50:51], s[46:47], 0, v[142:143]
	s_mov_b32 m0, s21
	s_nop 0
	global_load_lds_dwordx4 v[50:51], off
	s_waitcnt lgkmcnt(8)
	s_barrier
	s_waitcnt lgkmcnt(0)
	s_waitcnt lgkmcnt(0)
	v_mfma_f32_16x16x32_bf16 v[50:53], v[2:5], v[18:21], 0
	v_mfma_f32_16x16x32_bf16 v[54:57], v[10:13], v[18:21], 0
	v_mfma_f32_16x16x32_bf16 v[58:61], v[2:5], v[26:29], 0
	v_mfma_f32_16x16x32_bf16 v[62:65], v[10:13], v[26:29], 0
	v_mfma_f32_16x16x32_bf16 v[66:69], v[2:5], v[34:37], 0
	v_mfma_f32_16x16x32_bf16 v[70:73], v[10:13], v[34:37], 0
	v_mfma_f32_16x16x32_bf16 v[74:77], v[2:5], v[42:45], 0
	v_mfma_f32_16x16x32_bf16 v[78:81], v[10:13], v[42:45], 0
	v_mfma_f32_16x16x32_bf16 v[50:53], v[6:9], v[22:25], v[50:53]
	v_mfma_f32_16x16x32_bf16 v[54:57], v[14:17], v[22:25], v[54:57]
	v_mfma_f32_16x16x32_bf16 v[58:61], v[6:9], v[30:33], v[58:61]
	v_mfma_f32_16x16x32_bf16 v[62:65], v[14:17], v[30:33], v[62:65]
	v_mfma_f32_16x16x32_bf16 v[66:69], v[6:9], v[38:41], v[66:69]
	v_mfma_f32_16x16x32_bf16 v[70:73], v[14:17], v[38:41], v[70:73]
	v_mfma_f32_16x16x32_bf16 v[74:77], v[6:9], v[46:49], v[74:77]
	v_mfma_f32_16x16x32_bf16 v[78:81], v[14:17], v[46:49], v[78:81]
	s_barrier
	s_add_i32 s48, 0, 0x14000
	v_lshl_add_u64 v[170:171], s[30:31], 0, v[140:141]
	s_mov_b64 s[52:53], 0x100
	s_add_i32 s47, s23, s38
	v_add_u32_e32 v220, s48, v1
	v_lshl_add_u64 v[98:99], v[170:171], 0, s[52:53]
	s_mov_b32 m0, s47
	v_lshl_add_u64 v[186:187], s[30:31], 0, v[144:145]
	s_add_i32 s23, s47, 0x2000
	ds_read_b128 v[82:85], v220
	ds_read_b128 v[86:89], v220 offset:1024
	ds_read_b128 v[90:93], v220 offset:2048
	ds_read_b128 v[94:97], v220 offset:3072
	global_load_lds_dwordx4 v[98:99], off
	v_lshl_add_u64 v[98:99], v[186:187], 0, s[52:53]
	s_mov_b32 m0, s23
	s_nop 0
	global_load_lds_dwordx4 v[98:99], off
	s_barrier
	s_waitcnt lgkmcnt(0)
	s_waitcnt lgkmcnt(0)
	v_mfma_f32_16x16x32_bf16 v[98:101], v[82:85], v[18:21], 0
	v_mfma_f32_16x16x32_bf16 v[18:21], v[90:93], v[18:21], 0
	v_mfma_f32_16x16x32_bf16 v[98:101], v[86:89], v[22:25], v[98:101]
	v_mfma_f32_16x16x32_bf16 v[18:21], v[94:97], v[22:25], v[18:21]
	v_mfma_f32_16x16x32_bf16 v[22:25], v[82:85], v[26:29], 0
	v_mfma_f32_16x16x32_bf16 v[26:29], v[90:93], v[26:29], 0
	v_mfma_f32_16x16x32_bf16 v[22:25], v[86:89], v[30:33], v[22:25]
	v_mfma_f32_16x16x32_bf16 v[26:29], v[94:97], v[30:33], v[26:29]
	v_mfma_f32_16x16x32_bf16 v[30:33], v[82:85], v[34:37], 0
	v_mfma_f32_16x16x32_bf16 v[34:37], v[90:93], v[34:37], 0
	v_mfma_f32_16x16x32_bf16 v[30:33], v[86:89], v[38:41], v[30:33]
	v_mfma_f32_16x16x32_bf16 v[34:37], v[94:97], v[38:41], v[34:37]
	v_mfma_f32_16x16x32_bf16 v[38:41], v[82:85], v[42:45], 0
	v_mfma_f32_16x16x32_bf16 v[42:45], v[90:93], v[42:45], 0
	v_mfma_f32_16x16x32_bf16 v[38:41], v[86:89], v[46:49], v[38:41]
	v_mfma_f32_16x16x32_bf16 v[42:45], v[94:97], v[46:49], v[42:45]
	v_lshl_add_u64 v[188:189], s[28:29], 0, v[138:139]
	s_mov_b32 m0, s3
	v_lshl_add_u64 v[130:131], v[188:189], 0, s[52:53]
	v_lshl_add_u64 v[218:219], s[28:29], 0, v[142:143]
	s_barrier
	ds_read_b128 v[46:49], v172 offset:16384
	ds_read_b128 v[102:105], v172 offset:17408
	ds_read_b128 v[106:109], v172 offset:18432
	ds_read_b128 v[110:113], v172 offset:19456
	ds_read_b128 v[114:117], v172 offset:20480
	ds_read_b128 v[118:121], v172 offset:21504
	ds_read_b128 v[122:125], v172 offset:22528
	ds_read_b128 v[126:129], v172 offset:23552
	global_load_lds_dwordx4 v[130:131], off
	v_lshl_add_u64 v[130:131], v[218:219], 0, s[52:53]
	s_mov_b32 m0, s39
	s_nop 0
	global_load_lds_dwordx4 v[130:131], off
	s_barrier
	s_waitcnt lgkmcnt(0)
	s_waitcnt lgkmcnt(0)
	v_mfma_f32_16x16x32_bf16 v[130:133], v[2:5], v[46:49], 0
	v_mfma_f32_16x16x32_bf16 v[146:149], v[2:5], v[106:109], 0
	v_mfma_f32_16x16x32_bf16 v[154:157], v[2:5], v[114:117], 0
	v_mfma_f32_16x16x32_bf16 v[2:5], v[2:5], v[122:125], 0
	v_mfma_f32_16x16x32_bf16 v[130:133], v[6:9], v[102:105], v[130:133]
	v_mfma_f32_16x16x32_bf16 v[134:137], v[10:13], v[46:49], 0
	v_mfma_f32_16x16x32_bf16 v[146:149], v[6:9], v[110:113], v[146:149]
	v_mfma_f32_16x16x32_bf16 v[150:153], v[10:13], v[106:109], 0
	v_mfma_f32_16x16x32_bf16 v[154:157], v[6:9], v[118:121], v[154:157]
	v_mfma_f32_16x16x32_bf16 v[158:161], v[10:13], v[114:117], 0
	v_mfma_f32_16x16x32_bf16 v[2:5], v[6:9], v[126:129], v[2:5]
	v_mfma_f32_16x16x32_bf16 v[6:9], v[10:13], v[122:125], 0
	v_mfma_f32_16x16x32_bf16 v[134:137], v[14:17], v[102:105], v[134:137]
	v_mfma_f32_16x16x32_bf16 v[150:153], v[14:17], v[110:113], v[150:153]
	v_mfma_f32_16x16x32_bf16 v[158:161], v[14:17], v[118:121], v[158:161]
	v_mfma_f32_16x16x32_bf16 v[6:9], v[14:17], v[126:129], v[6:9]
	s_barrier
	s_add_u32 s52, s30, 0x10100
	s_addc_u32 s53, s31, 0
	s_add_i32 s48, s48, s38
	v_lshl_add_u64 v[10:11], s[52:53], 0, v[140:141]
	s_mov_b32 m0, s48
	s_add_i32 s46, s48, 0x2000
	global_load_lds_dwordx4 v[10:11], off
	v_lshl_add_u64 v[10:11], s[52:53], 0, v[144:145]
	s_mov_b32 m0, s46
	s_nop 0
	global_load_lds_dwordx4 v[10:11], off
	s_waitcnt vmcnt(6)
	s_barrier
	v_mfma_f32_16x16x32_bf16 v[10:13], v[82:85], v[46:49], 0
	v_mfma_f32_16x16x32_bf16 v[14:17], v[90:93], v[46:49], 0
	v_mfma_f32_16x16x32_bf16 v[10:13], v[86:89], v[102:105], v[10:13]
	v_mfma_f32_16x16x32_bf16 v[14:17], v[94:97], v[102:105], v[14:17]
	v_mfma_f32_16x16x32_bf16 v[46:49], v[82:85], v[106:109], 0
	v_mfma_f32_16x16x32_bf16 v[102:105], v[90:93], v[106:109], 0
	v_mfma_f32_16x16x32_bf16 v[106:109], v[82:85], v[114:117], 0
	v_mfma_f32_16x16x32_bf16 v[82:85], v[82:85], v[122:125], 0
	v_mfma_f32_16x16x32_bf16 v[46:49], v[86:89], v[110:113], v[46:49]
	v_mfma_f32_16x16x32_bf16 v[102:105], v[94:97], v[110:113], v[102:105]
	v_mfma_f32_16x16x32_bf16 v[106:109], v[86:89], v[118:121], v[106:109]
	v_mfma_f32_16x16x32_bf16 v[110:113], v[90:93], v[114:117], 0
	v_mfma_f32_16x16x32_bf16 v[82:85], v[86:89], v[126:129], v[82:85]
	v_mfma_f32_16x16x32_bf16 v[86:89], v[90:93], v[122:125], 0
	v_mfma_f32_16x16x32_bf16 v[110:113], v[94:97], v[118:121], v[110:113]
	v_mfma_f32_16x16x32_bf16 v[86:89], v[94:97], v[126:129], v[86:89]
	s_add_i32 s51, 0, 0x18000
	v_add_u32_e32 v232, s51, v1
	s_barrier
	ds_read_b128 v[90:93], v232
	ds_read_b128 v[94:97], v232 offset:1024
	ds_read_b128 v[114:117], v232 offset:2048
	ds_read_b128 v[118:121], v232 offset:3072
	s_add_u32 s52, s28, 0x40100
	s_addc_u32 s53, s29, 0
	s_mov_b32 m0, s40
	v_lshl_add_u64 v[202:203], s[52:53], 0, v[138:139]
	ds_read_b128 v[122:125], v172 offset:32768
	ds_read_b128 v[126:129], v172 offset:33792
	ds_read_b128 v[162:165], v172 offset:34816
	ds_read_b128 v[166:169], v172 offset:35840
	ds_read_b128 v[174:177], v172 offset:36864
	ds_read_b128 v[190:193], v172 offset:37888
	ds_read_b128 v[194:197], v172 offset:38912
	ds_read_b128 v[198:201], v172 offset:39936
	global_load_lds_dwordx4 v[202:203], off
	v_lshl_add_u64 v[202:203], s[52:53], 0, v[142:143]
	s_mov_b32 m0, s41
	s_nop 0
	global_load_lds_dwordx4 v[202:203], off
	s_waitcnt lgkmcnt(8)
	s_barrier
	s_waitcnt lgkmcnt(0)
	s_waitcnt lgkmcnt(0)
	v_mfma_f32_16x16x32_bf16 v[50:53], v[90:93], v[122:125], v[50:53]
	v_mfma_f32_16x16x32_bf16 v[54:57], v[114:117], v[122:125], v[54:57]
	v_mfma_f32_16x16x32_bf16 v[58:61], v[90:93], v[162:165], v[58:61]
	v_mfma_f32_16x16x32_bf16 v[62:65], v[114:117], v[162:165], v[62:65]
	v_mfma_f32_16x16x32_bf16 v[66:69], v[90:93], v[174:177], v[66:69]
	v_mfma_f32_16x16x32_bf16 v[70:73], v[114:117], v[174:177], v[70:73]
	v_mfma_f32_16x16x32_bf16 v[74:77], v[90:93], v[194:197], v[74:77]
	v_mfma_f32_16x16x32_bf16 v[78:81], v[114:117], v[194:197], v[78:81]
	v_mfma_f32_16x16x32_bf16 v[50:53], v[94:97], v[126:129], v[50:53]
	v_mfma_f32_16x16x32_bf16 v[54:57], v[118:121], v[126:129], v[54:57]
	v_mfma_f32_16x16x32_bf16 v[58:61], v[94:97], v[166:169], v[58:61]
	v_mfma_f32_16x16x32_bf16 v[62:65], v[118:121], v[166:169], v[62:65]
	v_mfma_f32_16x16x32_bf16 v[66:69], v[94:97], v[190:193], v[66:69]
	v_mfma_f32_16x16x32_bf16 v[70:73], v[118:121], v[190:193], v[70:73]
	v_mfma_f32_16x16x32_bf16 v[74:77], v[94:97], v[198:201], v[74:77]
	v_mfma_f32_16x16x32_bf16 v[78:81], v[118:121], v[198:201], v[78:81]
	s_barrier
	s_add_i32 s54, 0, 0x1c000
	s_mov_b64 s[52:53], 0x180
	s_add_i32 s51, s51, s38
	v_add_u32_e32 v233, s54, v1
	v_lshl_add_u64 v[170:171], v[170:171], 0, s[52:53]
	s_mov_b32 m0, s51
	s_add_i32 s49, s51, 0x2000
	ds_read_b128 v[202:205], v233
	ds_read_b128 v[206:209], v233 offset:1024
	ds_read_b128 v[210:213], v233 offset:2048
	ds_read_b128 v[214:217], v233 offset:3072
	global_load_lds_dwordx4 v[170:171], off
	v_lshl_add_u64 v[170:171], v[186:187], 0, s[52:53]
	s_mov_b32 m0, s49
	s_nop 0
	global_load_lds_dwordx4 v[170:171], off
	s_barrier
	s_waitcnt lgkmcnt(0)
	s_waitcnt lgkmcnt(0)
	v_mfma_f32_16x16x32_bf16 v[98:101], v[202:205], v[122:125], v[98:101]
	v_mfma_f32_16x16x32_bf16 v[18:21], v[210:213], v[122:125], v[18:21]
	v_mfma_f32_16x16x32_bf16 v[22:25], v[202:205], v[162:165], v[22:25]
	v_mfma_f32_16x16x32_bf16 v[26:29], v[210:213], v[162:165], v[26:29]
	v_mfma_f32_16x16x32_bf16 v[30:33], v[202:205], v[174:177], v[30:33]
	v_mfma_f32_16x16x32_bf16 v[34:37], v[210:213], v[174:177], v[34:37]
	v_mfma_f32_16x16x32_bf16 v[38:41], v[202:205], v[194:197], v[38:41]
	v_mfma_f32_16x16x32_bf16 v[42:45], v[210:213], v[194:197], v[42:45]
	v_mfma_f32_16x16x32_bf16 v[98:101], v[206:209], v[126:129], v[98:101]
	v_mfma_f32_16x16x32_bf16 v[18:21], v[214:217], v[126:129], v[18:21]
	v_mfma_f32_16x16x32_bf16 v[22:25], v[206:209], v[166:169], v[22:25]
	v_mfma_f32_16x16x32_bf16 v[26:29], v[214:217], v[166:169], v[26:29]
	v_mfma_f32_16x16x32_bf16 v[30:33], v[206:209], v[190:193], v[30:33]
	v_mfma_f32_16x16x32_bf16 v[34:37], v[214:217], v[190:193], v[34:37]
	v_mfma_f32_16x16x32_bf16 v[38:41], v[206:209], v[198:201], v[38:41]
	v_mfma_f32_16x16x32_bf16 v[42:45], v[214:217], v[198:201], v[42:45]
	s_mov_b32 m0, s42
	v_lshl_add_u64 v[170:171], v[188:189], 0, s[52:53]
	s_barrier
	ds_read_b128 v[122:125], v172 offset:49152
	ds_read_b128 v[126:129], v172 offset:50176
	ds_read_b128 v[162:165], v172 offset:51200
	ds_read_b128 v[166:169], v172 offset:52224
	ds_read_b128 v[174:177], v172 offset:53248
	ds_read_b128 v[190:193], v172 offset:54272
	ds_read_b128 v[194:197], v172 offset:55296
	ds_read_b128 v[198:201], v172 offset:56320
	global_load_lds_dwordx4 v[170:171], off
	v_lshl_add_u64 v[170:171], v[218:219], 0, s[52:53]
	s_mov_b32 m0, s43
	s_nop 0
	global_load_lds_dwordx4 v[170:171], off
	s_barrier
	s_waitcnt lgkmcnt(0)
	s_waitcnt lgkmcnt(0)
	v_mfma_f32_16x16x32_bf16 v[130:133], v[90:93], v[122:125], v[130:133]
	v_mfma_f32_16x16x32_bf16 v[134:137], v[114:117], v[122:125], v[134:137]
	v_mfma_f32_16x16x32_bf16 v[146:149], v[90:93], v[162:165], v[146:149]
	v_mfma_f32_16x16x32_bf16 v[150:153], v[114:117], v[162:165], v[150:153]
	v_mfma_f32_16x16x32_bf16 v[154:157], v[90:93], v[174:177], v[154:157]
	v_mfma_f32_16x16x32_bf16 v[158:161], v[114:117], v[174:177], v[158:161]
	v_mfma_f32_16x16x32_bf16 v[2:5], v[90:93], v[194:197], v[2:5]
	v_mfma_f32_16x16x32_bf16 v[6:9], v[114:117], v[194:197], v[6:9]
	v_mfma_f32_16x16x32_bf16 v[130:133], v[94:97], v[126:129], v[130:133]
	v_mfma_f32_16x16x32_bf16 v[134:137], v[118:121], v[126:129], v[134:137]
	v_mfma_f32_16x16x32_bf16 v[146:149], v[94:97], v[166:169], v[146:149]
	v_mfma_f32_16x16x32_bf16 v[150:153], v[118:121], v[166:169], v[150:153]
	v_mfma_f32_16x16x32_bf16 v[154:157], v[94:97], v[190:193], v[154:157]
	v_mfma_f32_16x16x32_bf16 v[158:161], v[118:121], v[190:193], v[158:161]
	v_mfma_f32_16x16x32_bf16 v[2:5], v[94:97], v[198:201], v[2:5]
	v_mfma_f32_16x16x32_bf16 v[6:9], v[118:121], v[198:201], v[6:9]
	s_barrier
	s_add_u32 s52, s30, 0x10180
	s_addc_u32 s53, s31, 0
	s_add_i32 s31, s54, s38
	v_lshl_add_u64 v[90:91], s[52:53], 0, v[140:141]
	s_mov_b32 m0, s31
	s_add_i32 s30, s31, 0x2000
	global_load_lds_dwordx4 v[90:91], off
	v_lshl_add_u64 v[90:91], s[52:53], 0, v[144:145]
	s_mov_b32 m0, s30
	s_nop 0
	global_load_lds_dwordx4 v[90:91], off
	s_waitcnt vmcnt(6)
	s_barrier
	v_mfma_f32_16x16x32_bf16 v[10:13], v[202:205], v[122:125], v[10:13]
	v_mfma_f32_16x16x32_bf16 v[14:17], v[210:213], v[122:125], v[14:17]
	v_mfma_f32_16x16x32_bf16 v[46:49], v[202:205], v[162:165], v[46:49]
	v_mfma_f32_16x16x32_bf16 v[90:93], v[210:213], v[162:165], v[102:105]
	v_mfma_f32_16x16x32_bf16 v[94:97], v[202:205], v[174:177], v[106:109]
	v_mfma_f32_16x16x32_bf16 v[102:105], v[210:213], v[174:177], v[110:113]
	v_mfma_f32_16x16x32_bf16 v[82:85], v[202:205], v[194:197], v[82:85]
	v_mfma_f32_16x16x32_bf16 v[86:89], v[210:213], v[194:197], v[86:89]
	v_mfma_f32_16x16x32_bf16 v[10:13], v[206:209], v[126:129], v[10:13]
	v_mfma_f32_16x16x32_bf16 v[14:17], v[214:217], v[126:129], v[14:17]
	v_mfma_f32_16x16x32_bf16 v[46:49], v[206:209], v[166:169], v[46:49]
	v_mfma_f32_16x16x32_bf16 v[90:93], v[214:217], v[166:169], v[90:93]
	v_mfma_f32_16x16x32_bf16 v[94:97], v[206:209], v[190:193], v[94:97]
	v_mfma_f32_16x16x32_bf16 v[102:105], v[214:217], v[190:193], v[102:105]
	v_mfma_f32_16x16x32_bf16 v[82:85], v[206:209], v[198:201], v[82:85]
	v_mfma_f32_16x16x32_bf16 v[86:89], v[214:217], v[198:201], v[86:89]
	s_barrier
	ds_read_b128 v[106:109], v173
	ds_read_b128 v[110:113], v173 offset:1024
	ds_read_b128 v[114:117], v173 offset:2048
	ds_read_b128 v[118:121], v173 offset:3072
	s_add_u32 s28, s28, 0x40180
	s_addc_u32 s29, s29, 0
	s_mov_b32 m0, s50
	v_lshl_add_u64 v[170:171], s[28:29], 0, v[138:139]
	ds_read_b128 v[122:125], v172
	ds_read_b128 v[126:129], v172 offset:1024
	ds_read_b128 v[162:165], v172 offset:2048
	ds_read_b128 v[166:169], v172 offset:3072
	ds_read_b128 v[174:177], v172 offset:4096
	ds_read_b128 v[190:193], v172 offset:5120
	ds_read_b128 v[194:197], v172 offset:6144
	ds_read_b128 v[198:201], v172 offset:7168
	global_load_lds_dwordx4 v[170:171], off
	v_lshl_add_u64 v[170:171], s[28:29], 0, v[142:143]
	s_mov_b32 m0, s21
	s_nop 0
	global_load_lds_dwordx4 v[170:171], off
	s_waitcnt lgkmcnt(8)
	s_barrier
	s_waitcnt lgkmcnt(0)
	s_waitcnt lgkmcnt(0)
	v_mfma_f32_16x16x32_bf16 v[58:61], v[106:109], v[162:165], v[58:61]
	v_mfma_f32_16x16x32_bf16 v[202:205], v[110:113], v[166:169], v[58:61]
	v_mfma_f32_16x16x32_bf16 v[58:61], v[114:117], v[162:165], v[62:65]
	v_mfma_f32_16x16x32_bf16 v[62:65], v[118:121], v[166:169], v[58:61]
	v_mfma_f32_16x16x32_bf16 v[58:61], v[106:109], v[174:177], v[66:69]
	v_mfma_f32_16x16x32_bf16 v[66:69], v[110:113], v[190:193], v[58:61]
	v_mfma_f32_16x16x32_bf16 v[58:61], v[114:117], v[174:177], v[70:73]
	v_mfma_f32_16x16x32_bf16 v[70:73], v[118:121], v[190:193], v[58:61]
	v_mfma_f32_16x16x32_bf16 v[58:61], v[106:109], v[194:197], v[74:77]
	v_mfma_f32_16x16x32_bf16 v[50:53], v[106:109], v[122:125], v[50:53]
	v_mfma_f32_16x16x32_bf16 v[54:57], v[114:117], v[122:125], v[54:57]
	v_mfma_f32_16x16x32_bf16 v[74:77], v[110:113], v[198:201], v[58:61]
	v_mfma_f32_16x16x32_bf16 v[58:61], v[114:117], v[194:197], v[78:81]
	v_mfma_f32_16x16x32_bf16 v[50:53], v[110:113], v[126:129], v[50:53]
	v_mfma_f32_16x16x32_bf16 v[54:57], v[118:121], v[126:129], v[54:57]
	v_mfma_f32_16x16x32_bf16 v[78:81], v[118:121], v[198:201], v[58:61]
	s_barrier
	s_mov_b32 m0, s47
	v_lshl_add_u64 v[170:171], s[6:7], 0, v[140:141]
	s_nop 0
	ds_read_b128 v[58:61], v220
	ds_read_b128 v[206:209], v220 offset:1024
	ds_read_b128 v[210:213], v220 offset:2048
	ds_read_b128 v[214:217], v220 offset:3072
	global_load_lds_dwordx4 v[170:171], off
	v_lshl_add_u64 v[230:231], s[6:7], 0, v[144:145]
	s_mov_b32 m0, s23
	s_nop 0
	global_load_lds_dwordx4 v[230:231], off
	s_barrier
	s_waitcnt lgkmcnt(0)
	s_waitcnt lgkmcnt(0)
	v_mfma_f32_16x16x32_bf16 v[34:37], v[210:213], v[174:177], v[34:37]
	v_mfma_f32_16x16x32_bf16 v[22:25], v[58:61], v[162:165], v[22:25]
	v_mfma_f32_16x16x32_bf16 v[26:29], v[210:213], v[162:165], v[26:29]
	v_mfma_f32_16x16x32_bf16 v[162:165], v[214:217], v[190:193], v[34:37]
	v_mfma_f32_16x16x32_bf16 v[34:37], v[58:61], v[194:197], v[38:41]
	v_mfma_f32_16x16x32_bf16 v[98:101], v[58:61], v[122:125], v[98:101]
	v_mfma_f32_16x16x32_bf16 v[18:21], v[210:213], v[122:125], v[18:21]
	v_mfma_f32_16x16x32_bf16 v[30:33], v[58:61], v[174:177], v[30:33]
	v_mfma_f32_16x16x32_bf16 v[38:41], v[206:209], v[198:201], v[34:37]
	v_mfma_f32_16x16x32_bf16 v[34:37], v[210:213], v[194:197], v[42:45]
	v_mfma_f32_16x16x32_bf16 v[98:101], v[206:209], v[126:129], v[98:101]
	v_mfma_f32_16x16x32_bf16 v[18:21], v[214:217], v[126:129], v[18:21]
	v_mfma_f32_16x16x32_bf16 v[22:25], v[206:209], v[166:169], v[22:25]
	v_mfma_f32_16x16x32_bf16 v[26:29], v[214:217], v[166:169], v[26:29]
	v_mfma_f32_16x16x32_bf16 v[30:33], v[206:209], v[190:193], v[30:33]
	v_mfma_f32_16x16x32_bf16 v[166:169], v[214:217], v[198:201], v[34:37]
	s_mov_b32 m0, s3
	v_lshl_add_u64 v[252:253], s[24:25], 0, v[138:139]
	s_barrier
	ds_read_b128 v[34:37], v172 offset:16384
	ds_read_b128 v[42:45], v172 offset:17408
	ds_read_b128 v[122:125], v172 offset:18432
	ds_read_b128 v[126:129], v172 offset:19456
	ds_read_b128 v[174:177], v172 offset:20480
	ds_read_b128 v[190:193], v172 offset:21504
	ds_read_b128 v[194:197], v172 offset:22528
	ds_read_b128 v[198:201], v172 offset:23552
	global_load_lds_dwordx4 v[252:253], off
	v_lshl_add_u64 v[246:247], s[24:25], 0, v[142:143]
	s_mov_b32 m0, s39
	s_nop 0
	global_load_lds_dwordx4 v[246:247], off
	s_barrier
	s_waitcnt lgkmcnt(0)
	s_waitcnt lgkmcnt(0)
	v_mfma_f32_16x16x32_bf16 v[130:133], v[106:109], v[34:37], v[130:133]
	v_mfma_f32_16x16x32_bf16 v[218:221], v[110:113], v[42:45], v[130:133]
	v_mfma_f32_16x16x32_bf16 v[130:133], v[114:117], v[34:37], v[134:137]
	v_mfma_f32_16x16x32_bf16 v[222:225], v[118:121], v[42:45], v[130:133]
	v_mfma_f32_16x16x32_bf16 v[130:133], v[106:109], v[122:125], v[146:149]
	v_mfma_f32_16x16x32_bf16 v[146:149], v[110:113], v[126:129], v[130:133]
	v_mfma_f32_16x16x32_bf16 v[130:133], v[114:117], v[122:125], v[150:153]
	v_mfma_f32_16x16x32_bf16 v[150:153], v[118:121], v[126:129], v[130:133]
	v_mfma_f32_16x16x32_bf16 v[130:133], v[106:109], v[174:177], v[154:157]
	v_mfma_f32_16x16x32_bf16 v[154:157], v[110:113], v[190:193], v[130:133]
	v_mfma_f32_16x16x32_bf16 v[130:133], v[114:117], v[174:177], v[158:161]
	v_mfma_f32_16x16x32_bf16 v[2:5], v[106:109], v[194:197], v[2:5]
	v_mfma_f32_16x16x32_bf16 v[6:9], v[114:117], v[194:197], v[6:9]
	v_mfma_f32_16x16x32_bf16 v[158:161], v[118:121], v[190:193], v[130:133]
	v_mfma_f32_16x16x32_bf16 v[2:5], v[110:113], v[198:201], v[2:5]
	v_mfma_f32_16x16x32_bf16 v[6:9], v[118:121], v[198:201], v[6:9]
	s_barrier
	s_add_u32 s28, s6, 0x10000
	s_addc_u32 s29, s7, 0
	s_mov_b32 m0, s48
	v_lshl_add_u64 v[106:107], s[28:29], 0, v[140:141]
	global_load_lds_dwordx4 v[106:107], off
	v_lshl_add_u64 v[106:107], s[28:29], 0, v[144:145]
	s_mov_b32 m0, s46
	s_nop 0
	global_load_lds_dwordx4 v[106:107], off
	s_waitcnt vmcnt(6)
	s_barrier
	v_mfma_f32_16x16x32_bf16 v[10:13], v[58:61], v[34:37], v[10:13]
	v_mfma_f32_16x16x32_bf16 v[226:229], v[206:209], v[42:45], v[10:13]
	v_mfma_f32_16x16x32_bf16 v[10:13], v[210:213], v[34:37], v[14:17]
	v_mfma_f32_16x16x32_bf16 v[14:17], v[214:217], v[42:45], v[10:13]
	v_mfma_f32_16x16x32_bf16 v[10:13], v[58:61], v[122:125], v[46:49]
	v_mfma_f32_16x16x32_bf16 v[248:251], v[206:209], v[126:129], v[10:13]
	v_mfma_f32_16x16x32_bf16 v[10:13], v[210:213], v[122:125], v[90:93]
	v_mfma_f32_16x16x32_bf16 v[236:239], v[214:217], v[126:129], v[10:13]
	v_mfma_f32_16x16x32_bf16 v[10:13], v[58:61], v[174:177], v[94:97]
	v_mfma_f32_16x16x32_bf16 v[186:189], v[206:209], v[190:193], v[10:13]
	v_mfma_f32_16x16x32_bf16 v[10:13], v[210:213], v[174:177], v[102:105]
	v_mfma_f32_16x16x32_bf16 v[174:177], v[214:217], v[190:193], v[10:13]
	v_mfma_f32_16x16x32_bf16 v[10:13], v[58:61], v[194:197], v[82:85]
	v_mfma_f32_16x16x32_bf16 v[190:193], v[206:209], v[198:201], v[10:13]
	v_mfma_f32_16x16x32_bf16 v[10:13], v[210:213], v[194:197], v[86:89]
	v_mfma_f32_16x16x32_bf16 v[194:197], v[214:217], v[198:201], v[10:13]
	s_barrier
	ds_read_b128 v[86:89], v232
	ds_read_b128 v[94:97], v232 offset:1024
	ds_read_b128 v[102:105], v232 offset:2048
	ds_read_b128 v[198:201], v232 offset:3072
	s_add_u32 s28, s24, 0x40000
	s_addc_u32 s29, s25, 0
	s_mov_b32 m0, s40
	v_lshl_add_u64 v[34:35], s[28:29], 0, v[138:139]
	ds_read_b128 v[10:13], v172 offset:32768
	ds_read_b128 v[46:49], v172 offset:33792
	ds_read_b128 v[82:85], v172 offset:34816
	ds_read_b128 v[90:93], v172 offset:35840
	ds_read_b128 v[110:113], v172 offset:36864
	ds_read_b128 v[206:209], v172 offset:37888
	ds_read_b128 v[210:213], v172 offset:38912
	ds_read_b128 v[214:217], v172 offset:39936
	global_load_lds_dwordx4 v[34:35], off
	v_lshl_add_u64 v[34:35], s[28:29], 0, v[142:143]
	s_mov_b32 m0, s41
	s_nop 0
	global_load_lds_dwordx4 v[34:35], off
	s_waitcnt lgkmcnt(8)
	s_barrier
	s_waitcnt lgkmcnt(0)
	s_waitcnt lgkmcnt(0)
	v_mfma_f32_16x16x32_bf16 v[34:37], v[86:89], v[10:13], v[50:53]
	v_mfma_f32_16x16x32_bf16 v[130:133], v[94:97], v[46:49], v[34:37]
	v_mfma_f32_16x16x32_bf16 v[34:37], v[102:105], v[10:13], v[54:57]
	v_mfma_f32_16x16x32_bf16 v[58:61], v[198:201], v[46:49], v[34:37]
	v_mfma_f32_16x16x32_bf16 v[34:37], v[86:89], v[82:85], v[202:205]
	v_mfma_f32_16x16x32_bf16 v[122:125], v[94:97], v[90:93], v[34:37]
	v_mfma_f32_16x16x32_bf16 v[34:37], v[102:105], v[82:85], v[62:65]
	v_mfma_f32_16x16x32_bf16 v[50:53], v[198:201], v[90:93], v[34:37]
	v_mfma_f32_16x16x32_bf16 v[34:37], v[86:89], v[110:113], v[66:69]
	v_mfma_f32_16x16x32_bf16 v[114:117], v[94:97], v[206:209], v[34:37]
	v_mfma_f32_16x16x32_bf16 v[34:37], v[102:105], v[110:113], v[70:73]
	v_mfma_f32_16x16x32_bf16 v[42:45], v[198:201], v[206:209], v[34:37]
	v_mfma_f32_16x16x32_bf16 v[34:37], v[86:89], v[210:213], v[74:77]
	v_mfma_f32_16x16x32_bf16 v[106:109], v[94:97], v[214:217], v[34:37]
	v_mfma_f32_16x16x32_bf16 v[34:37], v[102:105], v[210:213], v[78:81]
	v_mfma_f32_16x16x32_bf16 v[34:37], v[198:201], v[214:217], v[34:37]
	s_barrier
	s_mov_b32 m0, s51
	v_lshl_add_u64 v[54:55], v[170:171], 0, s[0:1]
	ds_read_b128 v[70:73], v233
	ds_read_b128 v[74:77], v233 offset:1024
	ds_read_b128 v[78:81], v233 offset:2048
	ds_read_b128 v[202:205], v233 offset:3072
	global_load_lds_dwordx4 v[54:55], off
	v_lshl_add_u64 v[54:55], v[230:231], 0, s[0:1]
	s_mov_b32 m0, s49
	s_nop 0
	global_load_lds_dwordx4 v[54:55], off
	s_barrier
	s_waitcnt lgkmcnt(0)
	s_waitcnt lgkmcnt(0)
	v_mfma_f32_16x16x32_bf16 v[54:57], v[70:73], v[10:13], v[98:101]
	v_mfma_f32_16x16x32_bf16 v[10:13], v[78:81], v[10:13], v[18:21]
	v_mfma_f32_16x16x32_bf16 v[62:65], v[202:205], v[46:49], v[10:13]
	v_mfma_f32_16x16x32_bf16 v[10:13], v[70:73], v[82:85], v[22:25]
	v_mfma_f32_16x16x32_bf16 v[126:129], v[74:77], v[90:93], v[10:13]
	v_mfma_f32_16x16x32_bf16 v[10:13], v[78:81], v[82:85], v[26:29]
	v_mfma_f32_16x16x32_bf16 v[134:137], v[74:77], v[46:49], v[54:57]
	v_mfma_f32_16x16x32_bf16 v[54:57], v[202:205], v[90:93], v[10:13]
	v_mfma_f32_16x16x32_bf16 v[10:13], v[70:73], v[110:113], v[30:33]
	v_mfma_f32_16x16x32_bf16 v[118:121], v[74:77], v[206:209], v[10:13]
	v_mfma_f32_16x16x32_bf16 v[10:13], v[78:81], v[110:113], v[162:165]
	v_mfma_f32_16x16x32_bf16 v[46:49], v[202:205], v[206:209], v[10:13]
	v_mfma_f32_16x16x32_bf16 v[10:13], v[70:73], v[210:213], v[38:41]
	v_mfma_f32_16x16x32_bf16 v[110:113], v[74:77], v[214:217], v[10:13]
	v_mfma_f32_16x16x32_bf16 v[10:13], v[78:81], v[210:213], v[166:169]
	v_mfma_f32_16x16x32_bf16 v[38:41], v[202:205], v[214:217], v[10:13]
	s_mov_b32 m0, s42
	s_nop 4
	v_lshl_add_u64 v[10:11], v[252:253], 0, s[0:1]
	s_barrier
	ds_read_b128 v[22:25], v172 offset:49152
	ds_read_b128 v[30:33], v172 offset:50176
	ds_read_b128 v[162:165], v172 offset:51200
	ds_read_b128 v[166:169], v172 offset:52224
	ds_read_b128 v[206:209], v172 offset:53248
	ds_read_b128 v[210:213], v172 offset:54272
	ds_read_b128 v[214:217], v172 offset:55296
	ds_read_b128 v[230:233], v172 offset:56320
	global_load_lds_dwordx4 v[10:11], off
	v_lshl_add_u64 v[10:11], v[246:247], 0, s[0:1]
	s_mov_b32 m0, s43
	s_nop 0
	global_load_lds_dwordx4 v[10:11], off
	s_barrier
	s_waitcnt lgkmcnt(0)
	s_waitcnt lgkmcnt(0)
	v_mfma_f32_16x16x32_bf16 v[10:13], v[86:89], v[22:25], v[218:221]
	v_mfma_f32_16x16x32_bf16 v[98:101], v[94:97], v[30:33], v[10:13]
	v_mfma_f32_16x16x32_bf16 v[10:13], v[102:105], v[22:25], v[222:225]
	v_mfma_f32_16x16x32_bf16 v[26:29], v[198:201], v[30:33], v[10:13]
	v_mfma_f32_16x16x32_bf16 v[10:13], v[86:89], v[162:165], v[146:149]
	v_mfma_f32_16x16x32_bf16 v[90:93], v[94:97], v[166:169], v[10:13]
	v_mfma_f32_16x16x32_bf16 v[10:13], v[102:105], v[162:165], v[150:153]
	v_mfma_f32_16x16x32_bf16 v[18:21], v[198:201], v[166:169], v[10:13]
	v_mfma_f32_16x16x32_bf16 v[10:13], v[86:89], v[206:209], v[154:157]
	v_mfma_f32_16x16x32_bf16 v[2:5], v[86:89], v[214:217], v[2:5]
	v_mfma_f32_16x16x32_bf16 v[82:85], v[94:97], v[210:213], v[10:13]
	v_mfma_f32_16x16x32_bf16 v[10:13], v[102:105], v[206:209], v[158:161]
	v_mfma_f32_16x16x32_bf16 v[66:69], v[94:97], v[230:233], v[2:5]
	v_mfma_f32_16x16x32_bf16 v[2:5], v[102:105], v[214:217], v[6:9]
	v_mfma_f32_16x16x32_bf16 v[10:13], v[198:201], v[210:213], v[10:13]
	v_mfma_f32_16x16x32_bf16 v[2:5], v[198:201], v[230:233], v[2:5]
	s_barrier
	s_add_u32 s6, s6, 0x10080
	s_addc_u32 s7, s7, 0
	s_mov_b32 m0, s31
	v_lshl_add_u64 v[6:7], s[6:7], 0, v[140:141]
	global_load_lds_dwordx4 v[6:7], off
	v_lshl_add_u64 v[6:7], s[6:7], 0, v[144:145]
	s_mov_b32 m0, s30
	s_nop 0
	global_load_lds_dwordx4 v[6:7], off
	s_waitcnt vmcnt(6)
	s_barrier
	v_mfma_f32_16x16x32_bf16 v[6:9], v[70:73], v[22:25], v[226:229]
	v_mfma_f32_16x16x32_bf16 v[102:105], v[74:77], v[30:33], v[6:9]
	v_mfma_f32_16x16x32_bf16 v[6:9], v[78:81], v[22:25], v[14:17]
	v_mfma_f32_16x16x32_bf16 v[30:33], v[202:205], v[30:33], v[6:9]
	v_mfma_f32_16x16x32_bf16 v[6:9], v[70:73], v[162:165], v[248:251]
	v_mfma_f32_16x16x32_bf16 v[94:97], v[74:77], v[166:169], v[6:9]
	v_mfma_f32_16x16x32_bf16 v[6:9], v[78:81], v[162:165], v[236:239]
	v_mfma_f32_16x16x32_bf16 v[22:25], v[202:205], v[166:169], v[6:9]
	v_mfma_f32_16x16x32_bf16 v[6:9], v[70:73], v[206:209], v[186:189]
	v_mfma_f32_16x16x32_bf16 v[86:89], v[74:77], v[210:213], v[6:9]
	v_mfma_f32_16x16x32_bf16 v[6:9], v[78:81], v[206:209], v[174:177]
	v_mfma_f32_16x16x32_bf16 v[14:17], v[202:205], v[210:213], v[6:9]
	v_mfma_f32_16x16x32_bf16 v[6:9], v[70:73], v[214:217], v[190:193]
	v_mfma_f32_16x16x32_bf16 v[70:73], v[74:77], v[230:233], v[6:9]
	v_mfma_f32_16x16x32_bf16 v[6:9], v[78:81], v[214:217], v[194:197]
	v_mfma_f32_16x16x32_bf16 v[6:9], v[202:205], v[230:233], v[6:9]
	v_mov_b32_e32 v74, v178
	s_barrier
	s_add_i32 s45, s45, s34
	v_ashrrev_i32_e32 v75, 2, v74
	v_and_b32_e32 v75, 0xffffffc0, v75
	v_lshl_add_u32 v75, s2, 8, v75
	v_and_or_b32 v148, v74, 15, v75
	v_lshrrev_b32_e32 v74, 1, v74
	v_and_b32_e32 v74, 0x78, v74
	v_lshl_or_b32 v150, s33, 7, v74
	v_ashrrev_i32_e32 v151, 31, v150
	v_lshlrev_b64 v[146:147], 2, v[150:151]
	v_lshl_add_u64 v[154:155], s[10:11], 0, v[146:147]
	global_load_dwordx4 v[158:161], v[154:155], off
	v_lshl_add_u64 v[152:153], s[16:17], 0, v[146:147]
	v_lshl_add_u64 v[156:157], s[8:9], 0, v[146:147]
	global_load_dwordx4 v[78:81], v[152:153], off
	global_load_dwordx4 v[74:77], v[156:157], off
	v_mov_b32_e32 v166, v148
	s_mov_b32 s2, 0xc1000000
	v_ashrrev_i32_e32 v167, 31, v166
	s_mov_b32 s33, s20
	s_mov_b64 s[30:31], s[26:27]
	s_mov_b64 s[28:29], s[24:25]
	s_waitcnt vmcnt(0)
	v_max_f32_e64 v146, -v158, -v158
	v_max_f32_e32 v162, 0, v146
	v_mul_f32_e64 v146, |v158|, s72
	v_exp_f32_e32 v146, v146
	v_add_f32_e32 v130, v130, v78
	v_add_f32_e32 v131, v131, v79
	v_mul_f32_e32 v130, 0xbfb8aa3b, v130
	v_add_f32_e32 v146, 1.0, v146
	v_cmp_gt_f32_e32 vcc, s71, v146
	v_mul_f32_e32 v131, 0xbfb8aa3b, v131
	v_exp_f32_e32 v130, v130
	v_cndmask_b32_e64 v147, 0, 32, vcc
	v_ldexp_f32 v146, v146, v147
	v_log_f32_e32 v146, v146
	v_exp_f32_e32 v131, v131
	v_add_f32_e32 v130, 1.0, v130
	v_rcp_f32_e32 v170, v130
	v_mul_f32_e32 v147, 0x3f317217, v146
	v_fma_f32 v147, v146, s73, -v147
	v_fmac_f32_e32 v147, 0x3377d1cf, v146
	v_fmac_f32_e32 v147, 0x3f317217, v146
	v_cmp_lt_f32_e64 s[6:7], |v146|, s74
	v_add_f32_e32 v131, 1.0, v131
	v_rcp_f32_e32 v171, v131
	v_cndmask_b32_e64 v146, v146, v147, s[6:7]
	v_cndmask_b32_e32 v147, 0, v243, vcc
	v_sub_f32_e32 v164, v146, v147
	v_max_f32_e64 v146, -v159, -v159
	v_max_f32_e32 v163, 0, v146
	v_mul_f32_e64 v146, |v159|, s72
	v_exp_f32_e32 v146, v146
	v_add_f32_e32 v130, v134, v74
	v_add_f32_e32 v131, v135, v75
	v_mul_f32_e32 v130, 0xbfb8aa3b, v130
	v_add_f32_e32 v146, 1.0, v146
	v_cmp_gt_f32_e32 vcc, s71, v146
	v_mul_f32_e32 v131, 0xbfb8aa3b, v131
	v_exp_f32_e32 v130, v130
	v_cndmask_b32_e64 v147, 0, 32, vcc
	v_ldexp_f32 v146, v146, v147
	v_log_f32_e32 v146, v146
	v_exp_f32_e32 v131, v131
	v_add_f32_e32 v130, 1.0, v130
	v_rcp_f32_e32 v130, v130
	v_mul_f32_e32 v147, 0x3f317217, v146
	v_fma_f32 v147, v146, s73, -v147
	v_fmac_f32_e32 v147, 0x3377d1cf, v146
	v_fmac_f32_e32 v147, 0x3f317217, v146
	v_cmp_lt_f32_e64 s[6:7], |v146|, s74
	v_add_f32_e32 v131, 1.0, v131
	v_rcp_f32_e32 v131, v131
	v_cndmask_b32_e64 v146, v146, v147, s[6:7]
	v_cndmask_b32_e32 v147, 0, v243, vcc
	v_sub_f32_e32 v165, v146, v147
	v_max_f32_e64 v146, -v160, -v160
	v_max_f32_e32 v158, 0, v146
	v_mul_f32_e64 v146, |v160|, s72
	v_exp_f32_e32 v146, v146
	v_pk_add_f32 v[134:135], v[162:163], v[164:165]
	v_add_f32_e32 v122, v122, v78
	v_pk_mul_f32 v[134:135], v[134:135], s[2:3] op_sel_hi:[1,0]
	v_add_f32_e32 v146, 1.0, v146
	v_cmp_gt_f32_e32 vcc, s71, v146
	v_pk_mul_f32 v[162:163], v[170:171], v[134:135]
	v_add_f32_e32 v123, v123, v79
	v_cndmask_b32_e64 v147, 0, 32, vcc
	v_ldexp_f32 v146, v146, v147
	v_log_f32_e32 v146, v146
	v_add_f32_e32 v149, v162, v162
	v_mul_f32_e32 v149, 0x3fb8aa3b, v149
	v_exp_f32_e32 v149, v149
	v_mul_f32_e32 v147, 0x3f317217, v146
	v_fma_f32 v147, v146, s73, -v147
	v_fmac_f32_e32 v147, 0x3377d1cf, v146
	v_fmac_f32_e32 v147, 0x3f317217, v146
	v_cmp_lt_f32_e64 s[6:7], |v146|, s74
	v_sub_f32_e32 v149, 1.0, v149
	v_max_f32_e32 v149, 0, v149
	v_cndmask_b32_e64 v146, v146, v147, s[6:7]
	v_cndmask_b32_e32 v147, 0, v243, vcc
	v_sub_f32_e32 v160, v146, v147
	v_max_f32_e64 v146, -v161, -v161
	v_max_f32_e32 v159, 0, v146
	v_mul_f32_e64 v146, |v161|, s72
	v_exp_f32_e32 v146, v146
	v_sqrt_f32_e32 v164, v149
	v_add_f32_e32 v149, v163, v163
	v_mul_f32_e32 v149, 0x3fb8aa3b, v149
	v_add_f32_e32 v146, 1.0, v146
	v_cmp_gt_f32_e32 vcc, s71, v146
	v_exp_f32_e32 v149, v149
	v_mul_f32_e32 v122, 0xbfb8aa3b, v122
	v_cndmask_b32_e64 v147, 0, 32, vcc
	v_ldexp_f32 v146, v146, v147
	v_log_f32_e32 v146, v146
	v_sub_f32_e32 v149, 1.0, v149
	v_max_f32_e32 v149, 0, v149
	v_sqrt_f32_e32 v165, v149
	v_mul_f32_e32 v147, 0x3f317217, v146
	v_fma_f32 v147, v146, s73, -v147
	v_fmac_f32_e32 v147, 0x3377d1cf, v146
	v_fmac_f32_e32 v147, 0x3f317217, v146
	v_cmp_lt_f32_e64 s[6:7], |v146|, s74
	v_pk_mul_f32 v[130:131], v[130:131], v[164:165]
	v_mul_f32_e32 v123, 0xbfb8aa3b, v123
	v_cndmask_b32_e64 v146, v146, v147, s[6:7]
	v_cndmask_b32_e32 v147, 0, v243, vcc
	v_sub_f32_e32 v161, v146, v147
	v_lshlrev_b64 v[146:147], 11, v[166:167]
	v_lshl_add_u64 v[168:169], s[14:15], 0, v[146:147]
	v_lshlrev_b64 v[146:147], 1, v[150:151]
	v_lshl_add_u64 v[168:169], v[168:169], 0, v[146:147]
	global_load_dwordx2 v[168:169], v[168:169], off
	v_exp_f32_e32 v122, v122
	v_exp_f32_e32 v123, v123
	v_add_f32_e32 v126, v126, v74
	v_add_f32_e32 v127, v127, v75
	v_add_f32_e32 v122, 1.0, v122
	v_add_f32_e32 v123, 1.0, v123
	v_rcp_f32_e32 v122, v122
	v_rcp_f32_e32 v123, v123
	v_mul_f32_e32 v126, 0xbfb8aa3b, v126
	v_mul_f32_e32 v127, 0xbfb8aa3b, v127
	v_exp_f32_e32 v126, v126
	v_exp_f32_e32 v127, v127
	v_add_f32_e32 v114, v114, v78
	v_add_f32_e32 v115, v115, v79
	v_add_f32_e32 v126, 1.0, v126
	v_add_f32_e32 v127, 1.0, v127
	v_rcp_f32_e32 v126, v126
	v_rcp_f32_e32 v127, v127
	v_mul_f32_e32 v114, 0xbfb8aa3b, v114
	v_mul_f32_e32 v115, 0xbfb8aa3b, v115
	v_exp_f32_e32 v114, v114
	v_exp_f32_e32 v115, v115
	v_add_f32_e32 v118, v118, v74
	v_add_f32_e32 v119, v119, v75
	v_add_f32_e32 v114, 1.0, v114
	v_add_f32_e32 v115, 1.0, v115
	v_rcp_f32_e32 v114, v114
	v_rcp_f32_e32 v115, v115
	v_mul_f32_e32 v118, 0xbfb8aa3b, v118
	v_mul_f32_e32 v119, 0xbfb8aa3b, v119
	v_exp_f32_e32 v118, v118
	v_exp_f32_e32 v119, v119
	v_add_f32_e32 v106, v106, v78
	v_add_f32_e32 v107, v107, v79
	v_add_f32_e32 v118, 1.0, v118
	v_add_f32_e32 v119, 1.0, v119
	v_rcp_f32_e32 v118, v118
	v_rcp_f32_e32 v119, v119
	v_mul_f32_e32 v106, 0xbfb8aa3b, v106
	v_mul_f32_e32 v107, 0xbfb8aa3b, v107
	v_exp_f32_e32 v106, v106
	v_exp_f32_e32 v107, v107
	v_add_f32_e32 v110, v110, v74
	v_add_f32_e32 v111, v111, v75
	v_add_f32_e32 v106, 1.0, v106
	v_add_f32_e32 v107, 1.0, v107
	v_rcp_f32_e32 v106, v106
	v_rcp_f32_e32 v107, v107
	v_mul_f32_e32 v110, 0xbfb8aa3b, v110
	v_mul_f32_e32 v111, 0xbfb8aa3b, v111
	v_exp_f32_e32 v110, v110
	v_exp_f32_e32 v111, v111
	v_add_f32_e32 v98, v98, v78
	v_add_f32_e32 v99, v99, v79
	v_add_f32_e32 v110, 1.0, v110
	v_add_f32_e32 v111, 1.0, v111
	v_rcp_f32_e32 v110, v110
	v_rcp_f32_e32 v111, v111
	v_mul_f32_e32 v98, 0xbfb8aa3b, v98
	v_mul_f32_e32 v99, 0xbfb8aa3b, v99
	v_exp_f32_e32 v98, v98
	v_exp_f32_e32 v99, v99
	v_add_f32_e32 v102, v102, v74
	v_add_f32_e32 v103, v103, v75
	v_add_f32_e32 v98, 1.0, v98
	v_add_f32_e32 v99, 1.0, v99
	v_rcp_f32_e32 v98, v98
	v_rcp_f32_e32 v99, v99
	v_mul_f32_e32 v102, 0xbfb8aa3b, v102
	v_mul_f32_e32 v103, 0xbfb8aa3b, v103
	v_exp_f32_e32 v102, v102
	v_exp_f32_e32 v103, v103
	v_add_f32_e32 v90, v90, v78
	v_add_f32_e32 v91, v91, v79
	v_add_f32_e32 v102, 1.0, v102
	v_add_f32_e32 v103, 1.0, v103
	v_rcp_f32_e32 v102, v102
	v_rcp_f32_e32 v103, v103
	v_mul_f32_e32 v90, 0xbfb8aa3b, v90
	s_waitcnt vmcnt(0)
	v_lshlrev_b32_e32 v170, 16, v168
	v_and_b32_e32 v171, 0xffff0000, v168
	v_pk_mul_f32 v[164:165], v[130:131], v[170:171]
	v_add_f32_e32 v131, v136, v76
	v_mul_f32_e32 v131, 0xbfb8aa3b, v131
	v_exp_f32_e32 v131, v131
	v_add_f32_e32 v130, v132, v80
	v_mul_f32_e32 v130, 0xbfb8aa3b, v130
	v_exp_f32_e32 v130, v130
	v_add_f32_e32 v131, 1.0, v131
	v_rcp_f32_e32 v136, v131
	v_add_f32_e32 v131, v133, v81
	v_mul_f32_e32 v131, 0xbfb8aa3b, v131
	v_exp_f32_e32 v131, v131
	v_add_f32_e32 v132, v137, v77
	v_mul_f32_e32 v132, 0xbfb8aa3b, v132
	v_exp_f32_e32 v132, v132
	v_add_f32_e32 v130, 1.0, v130
	v_add_f32_e32 v131, 1.0, v131
	v_rcp_f32_e32 v130, v130
	v_rcp_f32_e32 v131, v131
	v_add_f32_e32 v132, 1.0, v132
	v_rcp_f32_e32 v137, v132
	v_pk_add_f32 v[132:133], v[158:159], v[160:161]
	v_lshlrev_b32_e32 v160, 16, v169
	v_pk_mul_f32 v[132:133], v[132:133], s[2:3] op_sel_hi:[1,0]
	v_and_b32_e32 v161, 0xffff0000, v169
	v_pk_mul_f32 v[130:131], v[130:131], v[132:133]
	v_mul_f32_e32 v91, 0xbfb8aa3b, v91
	v_add_f32_e32 v149, v130, v130
	v_mul_f32_e32 v149, 0x3fb8aa3b, v149
	v_exp_f32_e32 v149, v149
	v_exp_f32_e32 v90, v90
	v_exp_f32_e32 v91, v91
	v_add_f32_e32 v94, v94, v74
	v_sub_f32_e32 v149, 1.0, v149
	v_max_f32_e32 v149, 0, v149
	v_sqrt_f32_e32 v158, v149
	v_add_f32_e32 v149, v131, v131
	v_mul_f32_e32 v149, 0x3fb8aa3b, v149
	v_exp_f32_e32 v149, v149
	v_add_f32_e32 v90, 1.0, v90
	v_add_f32_e32 v91, 1.0, v91
	v_rcp_f32_e32 v90, v90
	v_sub_f32_e32 v149, 1.0, v149
	v_max_f32_e32 v149, 0, v149
	v_sqrt_f32_e32 v159, v149
	v_rcp_f32_e32 v91, v91
	v_add_f32_e32 v95, v95, v75
	v_mul_f32_e32 v94, 0xbfb8aa3b, v94
	v_pk_mul_f32 v[136:137], v[136:137], v[158:159]
	v_mul_f32_e32 v95, 0xbfb8aa3b, v95
	v_pk_mul_f32 v[158:159], v[136:137], v[160:161]
	v_cvt_pk_bf16_f32 v161, v130, v131
	v_mov_b64_e32 v[130:131], s[18:19]
	v_cvt_pk_bf16_f32 v160, v162, v163
	v_mad_i64_i32 v[162:163], s[6:7], v166, s84, v[130:131]
	v_lshl_add_u64 v[162:163], v[162:163], 0, v[146:147]
	v_add_co_u32_e32 v162, vcc, s69, v162
	v_add_u32_e32 v136, 16, v166
	s_nop 0
	v_addc_co_u32_e32 v163, vcc, 0, v163, vcc
	global_store_dwordx2 v[162:163], v[160:161], off offset:2048
	v_cvt_pk_bf16_f32 v160, v164, v165
	v_cvt_pk_bf16_f32 v161, v158, v159
	global_store_dwordx2 v[162:163], v[160:161], off
	v_pk_mul_f32 v[160:161], v[122:123], v[134:135]
	v_ashrrev_i32_e32 v137, 31, v136
	v_lshlrev_b64 v[158:159], 11, v[136:137]
	v_lshl_add_u64 v[158:159], s[14:15], 0, v[158:159]
	v_lshl_add_u64 v[158:159], v[158:159], 0, v[146:147]
	global_load_dwordx2 v[158:159], v[158:159], off
	v_add_f32_e32 v122, v160, v160
	v_add_f32_e32 v123, v161, v161
	v_mul_f32_e32 v122, 0x3fb8aa3b, v122
	v_mul_f32_e32 v123, 0x3fb8aa3b, v123
	v_exp_f32_e32 v122, v122
	v_exp_f32_e32 v123, v123
	v_exp_f32_e32 v94, v94
	v_exp_f32_e32 v95, v95
	v_sub_f32_e32 v122, 1.0, v122
	v_sub_f32_e32 v123, 1.0, v123
	v_max_f32_e32 v122, 0, v122
	v_max_f32_e32 v123, 0, v123
	v_sqrt_f32_e32 v122, v122
	v_sqrt_f32_e32 v123, v123
	v_add_f32_e32 v94, 1.0, v94
	v_add_f32_e32 v95, 1.0, v95
	v_rcp_f32_e32 v94, v94
	v_pk_mul_f32 v[122:123], v[126:127], v[122:123]
	v_rcp_f32_e32 v95, v95
	v_add_f32_e32 v82, v82, v78
	v_add_f32_e32 v83, v83, v79
	v_mul_f32_e32 v82, 0xbfb8aa3b, v82
	v_mul_f32_e32 v83, 0xbfb8aa3b, v83
	v_exp_f32_e32 v82, v82
	v_exp_f32_e32 v83, v83
	v_add_f32_e32 v86, v86, v74
	v_add_f32_e32 v87, v87, v75
	v_add_f32_e32 v82, 1.0, v82
	v_add_f32_e32 v83, 1.0, v83
	v_rcp_f32_e32 v82, v82
	v_rcp_f32_e32 v83, v83
	v_mul_f32_e32 v86, 0xbfb8aa3b, v86
	v_mul_f32_e32 v87, 0xbfb8aa3b, v87
	v_exp_f32_e32 v86, v86
	v_exp_f32_e32 v87, v87
	v_add_f32_e32 v66, v66, v78
	v_add_f32_e32 v67, v67, v79
	v_add_f32_e32 v86, 1.0, v86
	v_add_f32_e32 v87, 1.0, v87
	v_rcp_f32_e32 v86, v86
	v_rcp_f32_e32 v87, v87
	v_mul_f32_e32 v66, 0xbfb8aa3b, v66
	v_mul_f32_e32 v67, 0xbfb8aa3b, v67
	v_exp_f32_e32 v66, v66
	v_exp_f32_e32 v67, v67
	v_add_f32_e32 v70, v70, v74
	v_add_f32_e32 v71, v71, v75
	v_add_f32_e32 v66, 1.0, v66
	v_add_f32_e32 v67, 1.0, v67
	v_rcp_f32_e32 v66, v66
	v_rcp_f32_e32 v67, v67
	v_add_f32_e32 v68, v68, v80
	v_add_f32_e32 v69, v69, v81
	v_mul_f32_e32 v68, 0xbfb8aa3b, v68
	v_pk_mul_f32 v[66:67], v[66:67], v[134:135]
	v_mul_f32_e32 v69, 0xbfb8aa3b, v69
	v_add_f32_e32 v74, v66, v66
	v_add_f32_e32 v75, v67, v67
	v_mul_f32_e32 v74, 0x3fb8aa3b, v74
	v_mul_f32_e32 v75, 0x3fb8aa3b, v75
	v_mul_f32_e32 v70, 0xbfb8aa3b, v70
	v_mul_f32_e32 v71, 0xbfb8aa3b, v71
	v_exp_f32_e32 v74, v74
	v_exp_f32_e32 v75, v75
	v_exp_f32_e32 v68, v68
	v_exp_f32_e32 v69, v69
	v_exp_f32_e32 v70, v70
	v_exp_f32_e32 v71, v71
	v_sub_f32_e32 v74, 1.0, v74
	v_sub_f32_e32 v75, 1.0, v75
	v_add_f32_e32 v68, 1.0, v68
	v_add_f32_e32 v69, 1.0, v69
	v_add_f32_e32 v70, 1.0, v70
	v_add_f32_e32 v71, 1.0, v71
	v_max_f32_e32 v74, 0, v74
	v_max_f32_e32 v75, 0, v75
	v_rcp_f32_e32 v68, v68
	v_rcp_f32_e32 v69, v69
	v_rcp_f32_e32 v70, v70
	s_waitcnt vmcnt(0)
	v_lshlrev_b32_e32 v162, 16, v158
	v_and_b32_e32 v163, 0xffff0000, v158
	v_pk_mul_f32 v[126:127], v[122:123], v[162:163]
	v_add_f32_e32 v123, v128, v76
	v_mul_f32_e32 v123, 0xbfb8aa3b, v123
	v_exp_f32_e32 v123, v123
	v_add_f32_e32 v122, v124, v80
	v_mul_f32_e32 v122, 0xbfb8aa3b, v122
	v_exp_f32_e32 v122, v122
	v_add_f32_e32 v123, 1.0, v123
	v_rcp_f32_e32 v124, v123
	v_add_f32_e32 v123, v125, v81
	v_mul_f32_e32 v123, 0xbfb8aa3b, v123
	v_exp_f32_e32 v123, v123
	v_add_f32_e32 v122, 1.0, v122
	v_rcp_f32_e32 v122, v122
	v_add_f32_e32 v125, v129, v77
	v_add_f32_e32 v123, 1.0, v123
	v_rcp_f32_e32 v123, v123
	v_mul_f32_e32 v125, 0xbfb8aa3b, v125
	v_exp_f32_e32 v125, v125
	v_lshlrev_b32_e32 v158, 16, v159
	v_pk_mul_f32 v[128:129], v[122:123], v[132:133]
	v_and_b32_e32 v159, 0xffff0000, v159
	v_add_f32_e32 v122, v128, v128
	v_add_f32_e32 v123, v129, v129
	v_mul_f32_e32 v122, 0x3fb8aa3b, v122
	v_mul_f32_e32 v123, 0x3fb8aa3b, v123
	v_exp_f32_e32 v122, v122
	v_exp_f32_e32 v123, v123
	v_add_f32_e32 v125, 1.0, v125
	v_rcp_f32_e32 v125, v125
	v_sub_f32_e32 v122, 1.0, v122
	v_sub_f32_e32 v123, 1.0, v123
	v_max_f32_e32 v122, 0, v122
	v_max_f32_e32 v123, 0, v123
	v_sqrt_f32_e32 v122, v122
	v_sqrt_f32_e32 v123, v123
	v_cvt_pk_bf16_f32 v126, v126, v127
	v_rcp_f32_e32 v71, v71
	v_sqrt_f32_e32 v74, v74
	v_pk_mul_f32 v[122:123], v[124:125], v[122:123]
	v_sqrt_f32_e32 v75, v75
	v_pk_mul_f32 v[124:125], v[122:123], v[158:159]
	v_cvt_pk_bf16_f32 v159, v128, v129
	v_mad_i64_i32 v[128:129], s[6:7], v136, s84, v[130:131]
	v_lshl_add_u64 v[128:129], v[128:129], 0, v[146:147]
	v_add_co_u32_e32 v128, vcc, s69, v128
	v_add_u32_e32 v122, 16, v136
	v_cvt_pk_bf16_f32 v158, v160, v161
	v_addc_co_u32_e32 v129, vcc, 0, v129, vcc
	v_cvt_pk_bf16_f32 v127, v124, v125
	global_store_dwordx2 v[128:129], v[158:159], off offset:2048
	global_store_dwordx2 v[128:129], v[126:127], off
	v_pk_mul_f32 v[126:127], v[114:115], v[134:135]
	v_ashrrev_i32_e32 v123, 31, v122
	v_lshlrev_b64 v[124:125], 11, v[122:123]
	v_lshl_add_u64 v[124:125], s[14:15], 0, v[124:125]
	v_lshl_add_u64 v[124:125], v[124:125], 0, v[146:147]
	global_load_dwordx2 v[124:125], v[124:125], off
	v_add_f32_e32 v114, v126, v126
	v_add_f32_e32 v115, v127, v127
	v_mul_f32_e32 v114, 0x3fb8aa3b, v114
	v_mul_f32_e32 v115, 0x3fb8aa3b, v115
	v_exp_f32_e32 v114, v114
	v_exp_f32_e32 v115, v115
	v_pk_mul_f32 v[68:69], v[68:69], v[132:133]
	v_pk_mul_f32 v[70:71], v[70:71], v[74:75]
	v_sub_f32_e32 v114, 1.0, v114
	v_sub_f32_e32 v115, 1.0, v115
	v_max_f32_e32 v114, 0, v114
	v_max_f32_e32 v115, 0, v115
	v_sqrt_f32_e32 v114, v114
	v_sqrt_f32_e32 v115, v115
	v_add_f32_e32 v74, v68, v68
	v_add_f32_e32 v75, v69, v69
	v_add_f32_e32 v72, v72, v76
	v_pk_mul_f32 v[114:115], v[118:119], v[114:115]
	v_add_f32_e32 v73, v73, v77
	v_mul_f32_e32 v74, 0x3fb8aa3b, v74
	v_mul_f32_e32 v75, 0x3fb8aa3b, v75
	v_mul_f32_e32 v72, 0xbfb8aa3b, v72
	v_mul_f32_e32 v73, 0xbfb8aa3b, v73
	v_exp_f32_e32 v74, v74
	v_exp_f32_e32 v75, v75
	v_exp_f32_e32 v72, v72
	v_exp_f32_e32 v73, v73
	v_sub_f32_e32 v74, 1.0, v74
	v_sub_f32_e32 v75, 1.0, v75
	v_add_f32_e32 v72, 1.0, v72
	v_add_f32_e32 v73, 1.0, v73
	v_max_f32_e32 v74, 0, v74
	v_max_f32_e32 v75, 0, v75
	v_rcp_f32_e32 v72, v72
	v_rcp_f32_e32 v73, v73
	v_sqrt_f32_e32 v74, v74
	v_sqrt_f32_e32 v75, v75
	v_cvt_pk_bf16_f32 v66, v66, v67
	v_cvt_pk_bf16_f32 v67, v68, v69
	v_pk_mul_f32 v[72:73], v[72:73], v[74:75]
	v_or_b32_e32 v74, 4, v150
	v_ashrrev_i32_e32 v75, 31, v74
	s_waitcnt vmcnt(0)
	v_lshlrev_b32_e32 v128, 16, v124
	v_and_b32_e32 v129, 0xffff0000, v124
	v_pk_mul_f32 v[118:119], v[114:115], v[128:129]
	v_add_f32_e32 v115, v120, v76
	v_mul_f32_e32 v115, 0xbfb8aa3b, v115
	v_exp_f32_e32 v115, v115
	v_add_f32_e32 v114, v116, v80
	v_mul_f32_e32 v114, 0xbfb8aa3b, v114
	v_exp_f32_e32 v114, v114
	v_add_f32_e32 v115, 1.0, v115
	v_rcp_f32_e32 v116, v115
	v_add_f32_e32 v115, v117, v81
	v_mul_f32_e32 v115, 0xbfb8aa3b, v115
	v_exp_f32_e32 v115, v115
	v_add_f32_e32 v114, 1.0, v114
	v_rcp_f32_e32 v114, v114
	v_add_f32_e32 v117, v121, v77
	v_add_f32_e32 v115, 1.0, v115
	v_rcp_f32_e32 v115, v115
	v_mul_f32_e32 v117, 0xbfb8aa3b, v117
	v_exp_f32_e32 v117, v117
	v_lshlrev_b32_e32 v124, 16, v125
	v_pk_mul_f32 v[120:121], v[114:115], v[132:133]
	v_and_b32_e32 v125, 0xffff0000, v125
	v_add_f32_e32 v114, v120, v120
	v_add_f32_e32 v115, v121, v121
	v_mul_f32_e32 v114, 0x3fb8aa3b, v114
	v_mul_f32_e32 v115, 0x3fb8aa3b, v115
	v_exp_f32_e32 v114, v114
	v_exp_f32_e32 v115, v115
	v_add_f32_e32 v117, 1.0, v117
	v_rcp_f32_e32 v117, v117
	v_sub_f32_e32 v114, 1.0, v114
	v_sub_f32_e32 v115, 1.0, v115
	v_max_f32_e32 v114, 0, v114
	v_max_f32_e32 v115, 0, v115
	v_sqrt_f32_e32 v114, v114
	v_sqrt_f32_e32 v115, v115
	v_cvt_pk_bf16_f32 v118, v118, v119
	v_pk_mul_f32 v[114:115], v[116:117], v[114:115]
	s_nop 0
	v_pk_mul_f32 v[116:117], v[114:115], v[124:125]
	v_cvt_pk_bf16_f32 v125, v120, v121
	v_mad_i64_i32 v[120:121], s[6:7], v122, s84, v[130:131]
	v_lshl_add_u64 v[120:121], v[120:121], 0, v[146:147]
	v_add_co_u32_e32 v120, vcc, s69, v120
	v_add_u32_e32 v114, 16, v122
	v_cvt_pk_bf16_f32 v124, v126, v127
	v_addc_co_u32_e32 v121, vcc, 0, v121, vcc
	v_cvt_pk_bf16_f32 v119, v116, v117
	global_store_dwordx2 v[120:121], v[124:125], off offset:2048
	global_store_dwordx2 v[120:121], v[118:119], off
	v_pk_mul_f32 v[118:119], v[106:107], v[134:135]
	v_ashrrev_i32_e32 v115, 31, v114
	v_lshlrev_b64 v[116:117], 11, v[114:115]
	v_lshl_add_u64 v[116:117], s[14:15], 0, v[116:117]
	v_lshl_add_u64 v[116:117], v[116:117], 0, v[146:147]
	global_load_dwordx2 v[116:117], v[116:117], off
	v_add_f32_e32 v106, v118, v118
	v_add_f32_e32 v107, v119, v119
	v_mul_f32_e32 v106, 0x3fb8aa3b, v106
	v_mul_f32_e32 v107, 0x3fb8aa3b, v107
	v_exp_f32_e32 v106, v106
	v_exp_f32_e32 v107, v107
	v_sub_f32_e32 v106, 1.0, v106
	v_sub_f32_e32 v107, 1.0, v107
	v_max_f32_e32 v106, 0, v106
	v_max_f32_e32 v107, 0, v107
	v_sqrt_f32_e32 v106, v106
	v_sqrt_f32_e32 v107, v107
	s_waitcnt vmcnt(0)
	v_lshlrev_b32_e32 v120, 16, v116
	v_and_b32_e32 v121, 0xffff0000, v116
	v_pk_mul_f32 v[106:107], v[110:111], v[106:107]
	v_lshlrev_b32_e32 v116, 16, v117
	v_pk_mul_f32 v[110:111], v[106:107], v[120:121]
	v_add_f32_e32 v107, v112, v76
	v_mul_f32_e32 v107, 0xbfb8aa3b, v107
	v_exp_f32_e32 v107, v107
	v_add_f32_e32 v106, v108, v80
	v_mul_f32_e32 v106, 0xbfb8aa3b, v106
	v_exp_f32_e32 v106, v106
	v_add_f32_e32 v107, 1.0, v107
	v_rcp_f32_e32 v108, v107
	v_add_f32_e32 v107, v109, v81
	v_mul_f32_e32 v107, 0xbfb8aa3b, v107
	v_exp_f32_e32 v107, v107
	v_add_f32_e32 v106, 1.0, v106
	v_rcp_f32_e32 v106, v106
	v_add_f32_e32 v109, v113, v77
	v_add_f32_e32 v107, 1.0, v107
	v_rcp_f32_e32 v107, v107
	v_mul_f32_e32 v109, 0xbfb8aa3b, v109
	v_exp_f32_e32 v109, v109
	v_and_b32_e32 v117, 0xffff0000, v117
	v_pk_mul_f32 v[112:113], v[106:107], v[132:133]
	v_cvt_pk_bf16_f32 v110, v110, v111
	v_add_f32_e32 v106, v112, v112
	v_add_f32_e32 v107, v113, v113
	v_mul_f32_e32 v106, 0x3fb8aa3b, v106
	v_mul_f32_e32 v107, 0x3fb8aa3b, v107
	v_exp_f32_e32 v106, v106
	v_exp_f32_e32 v107, v107
	v_add_f32_e32 v109, 1.0, v109
	v_rcp_f32_e32 v109, v109
	v_sub_f32_e32 v106, 1.0, v106
	v_sub_f32_e32 v107, 1.0, v107
	v_max_f32_e32 v106, 0, v106
	v_max_f32_e32 v107, 0, v107
	v_sqrt_f32_e32 v106, v106
	v_sqrt_f32_e32 v107, v107
	s_nop 0
	v_pk_mul_f32 v[106:107], v[108:109], v[106:107]
	s_nop 0
	v_pk_mul_f32 v[108:109], v[106:107], v[116:117]
	v_cvt_pk_bf16_f32 v117, v112, v113
	v_mad_i64_i32 v[112:113], s[6:7], v114, s84, v[130:131]
	v_lshl_add_u64 v[112:113], v[112:113], 0, v[146:147]
	v_add_co_u32_e32 v112, vcc, s69, v112
	v_add_u32_e32 v106, 0x50, v114
	v_cvt_pk_bf16_f32 v116, v118, v119
	v_addc_co_u32_e32 v113, vcc, 0, v113, vcc
	v_cvt_pk_bf16_f32 v111, v108, v109
	global_store_dwordx2 v[112:113], v[116:117], off offset:2048
	global_store_dwordx2 v[112:113], v[110:111], off
	v_pk_mul_f32 v[110:111], v[98:99], v[134:135]
	v_ashrrev_i32_e32 v107, 31, v106
	v_lshlrev_b64 v[108:109], 11, v[106:107]
	v_lshl_add_u64 v[108:109], s[14:15], 0, v[108:109]
	v_lshl_add_u64 v[108:109], v[108:109], 0, v[146:147]
	global_load_dwordx2 v[108:109], v[108:109], off
	v_add_f32_e32 v98, v110, v110
	v_add_f32_e32 v99, v111, v111
	v_mul_f32_e32 v98, 0x3fb8aa3b, v98
	v_mul_f32_e32 v99, 0x3fb8aa3b, v99
	v_exp_f32_e32 v98, v98
	v_exp_f32_e32 v99, v99
	v_sub_f32_e32 v98, 1.0, v98
	v_sub_f32_e32 v99, 1.0, v99
	v_max_f32_e32 v98, 0, v98
	v_max_f32_e32 v99, 0, v99
	v_sqrt_f32_e32 v98, v98
	v_sqrt_f32_e32 v99, v99
	s_waitcnt vmcnt(0)
	v_lshlrev_b32_e32 v112, 16, v108
	v_and_b32_e32 v113, 0xffff0000, v108
	v_pk_mul_f32 v[98:99], v[102:103], v[98:99]
	v_lshlrev_b32_e32 v108, 16, v109
	v_pk_mul_f32 v[102:103], v[98:99], v[112:113]
	v_add_f32_e32 v99, v104, v76
	v_mul_f32_e32 v99, 0xbfb8aa3b, v99
	v_exp_f32_e32 v99, v99
	v_add_f32_e32 v98, v100, v80
	v_mul_f32_e32 v98, 0xbfb8aa3b, v98
	v_exp_f32_e32 v98, v98
	v_add_f32_e32 v99, 1.0, v99
	v_rcp_f32_e32 v100, v99
	v_add_f32_e32 v99, v101, v81
	v_mul_f32_e32 v99, 0xbfb8aa3b, v99
	v_exp_f32_e32 v99, v99
	v_add_f32_e32 v98, 1.0, v98
	v_rcp_f32_e32 v98, v98
	v_add_f32_e32 v101, v105, v77
	v_add_f32_e32 v99, 1.0, v99
	v_rcp_f32_e32 v99, v99
	v_mul_f32_e32 v101, 0xbfb8aa3b, v101
	v_exp_f32_e32 v101, v101
	v_and_b32_e32 v109, 0xffff0000, v109
	v_pk_mul_f32 v[104:105], v[98:99], v[132:133]
	v_cvt_pk_bf16_f32 v102, v102, v103
	v_add_f32_e32 v98, v104, v104
	v_add_f32_e32 v99, v105, v105
	v_mul_f32_e32 v98, 0x3fb8aa3b, v98
	v_mul_f32_e32 v99, 0x3fb8aa3b, v99
	v_exp_f32_e32 v98, v98
	v_exp_f32_e32 v99, v99
	v_add_f32_e32 v101, 1.0, v101
	v_rcp_f32_e32 v101, v101
	v_sub_f32_e32 v98, 1.0, v98
	v_sub_f32_e32 v99, 1.0, v99
	v_max_f32_e32 v98, 0, v98
	v_max_f32_e32 v99, 0, v99
	v_sqrt_f32_e32 v98, v98
	v_sqrt_f32_e32 v99, v99
	s_nop 0
	v_pk_mul_f32 v[98:99], v[100:101], v[98:99]
	s_nop 0
	v_pk_mul_f32 v[100:101], v[98:99], v[108:109]
	v_cvt_pk_bf16_f32 v109, v104, v105
	v_mad_i64_i32 v[104:105], s[6:7], v106, s84, v[130:131]
	v_lshl_add_u64 v[104:105], v[104:105], 0, v[146:147]
	v_add_co_u32_e32 v104, vcc, s69, v104
	v_add_u32_e32 v98, 16, v106
	v_cvt_pk_bf16_f32 v108, v110, v111
	v_addc_co_u32_e32 v105, vcc, 0, v105, vcc
	v_cvt_pk_bf16_f32 v103, v100, v101
	global_store_dwordx2 v[104:105], v[108:109], off offset:2048
	global_store_dwordx2 v[104:105], v[102:103], off
	v_pk_mul_f32 v[102:103], v[90:91], v[134:135]
	v_ashrrev_i32_e32 v99, 31, v98
	v_lshlrev_b64 v[100:101], 11, v[98:99]
	v_lshl_add_u64 v[100:101], s[14:15], 0, v[100:101]
	v_lshl_add_u64 v[100:101], v[100:101], 0, v[146:147]
	global_load_dwordx2 v[100:101], v[100:101], off
	v_add_f32_e32 v90, v102, v102
	v_add_f32_e32 v91, v103, v103
	v_mul_f32_e32 v90, 0x3fb8aa3b, v90
	v_mul_f32_e32 v91, 0x3fb8aa3b, v91
	v_exp_f32_e32 v90, v90
	v_exp_f32_e32 v91, v91
	v_sub_f32_e32 v90, 1.0, v90
	v_sub_f32_e32 v91, 1.0, v91
	v_max_f32_e32 v90, 0, v90
	v_max_f32_e32 v91, 0, v91
	v_sqrt_f32_e32 v90, v90
	v_sqrt_f32_e32 v91, v91
	s_waitcnt vmcnt(0)
	v_lshlrev_b32_e32 v104, 16, v100
	v_and_b32_e32 v105, 0xffff0000, v100
	v_pk_mul_f32 v[90:91], v[94:95], v[90:91]
	v_lshlrev_b32_e32 v100, 16, v101
	v_pk_mul_f32 v[94:95], v[90:91], v[104:105]
	v_add_f32_e32 v91, v96, v76
	v_mul_f32_e32 v91, 0xbfb8aa3b, v91
	v_exp_f32_e32 v91, v91
	v_add_f32_e32 v90, v92, v80
	v_mul_f32_e32 v90, 0xbfb8aa3b, v90
	v_exp_f32_e32 v90, v90
	v_add_f32_e32 v91, 1.0, v91
	v_rcp_f32_e32 v92, v91
	v_add_f32_e32 v91, v93, v81
	v_mul_f32_e32 v91, 0xbfb8aa3b, v91
	v_exp_f32_e32 v91, v91
	v_add_f32_e32 v90, 1.0, v90
	v_rcp_f32_e32 v90, v90
	v_add_f32_e32 v93, v97, v77
	v_add_f32_e32 v91, 1.0, v91
	v_rcp_f32_e32 v91, v91
	v_mul_f32_e32 v93, 0xbfb8aa3b, v93
	v_exp_f32_e32 v93, v93
	v_and_b32_e32 v101, 0xffff0000, v101
	v_pk_mul_f32 v[96:97], v[90:91], v[132:133]
	v_cvt_pk_bf16_f32 v94, v94, v95
	v_add_f32_e32 v90, v96, v96
	v_add_f32_e32 v91, v97, v97
	v_mul_f32_e32 v90, 0x3fb8aa3b, v90
	v_mul_f32_e32 v91, 0x3fb8aa3b, v91
	v_exp_f32_e32 v90, v90
	v_exp_f32_e32 v91, v91
	v_add_f32_e32 v93, 1.0, v93
	v_rcp_f32_e32 v93, v93
	v_sub_f32_e32 v90, 1.0, v90
	v_sub_f32_e32 v91, 1.0, v91
	v_max_f32_e32 v90, 0, v90
	v_max_f32_e32 v91, 0, v91
	v_sqrt_f32_e32 v90, v90
	v_sqrt_f32_e32 v91, v91
	s_nop 0
	v_pk_mul_f32 v[90:91], v[92:93], v[90:91]
	s_nop 0
	v_pk_mul_f32 v[92:93], v[90:91], v[100:101]
	v_cvt_pk_bf16_f32 v101, v96, v97
	v_mad_i64_i32 v[96:97], s[6:7], v98, s84, v[130:131]
	v_lshl_add_u64 v[96:97], v[96:97], 0, v[146:147]
	v_add_co_u32_e32 v96, vcc, s69, v96
	v_add_u32_e32 v90, 16, v98
	v_cvt_pk_bf16_f32 v100, v102, v103
	v_addc_co_u32_e32 v97, vcc, 0, v97, vcc
	v_cvt_pk_bf16_f32 v95, v92, v93
	global_store_dwordx2 v[96:97], v[100:101], off offset:2048
	global_store_dwordx2 v[96:97], v[94:95], off
	v_pk_mul_f32 v[94:95], v[82:83], v[134:135]
	v_ashrrev_i32_e32 v91, 31, v90
	v_lshlrev_b64 v[92:93], 11, v[90:91]
	v_lshl_add_u64 v[92:93], s[14:15], 0, v[92:93]
	v_lshl_add_u64 v[92:93], v[92:93], 0, v[146:147]
	global_load_dwordx2 v[92:93], v[92:93], off
	v_add_f32_e32 v82, v94, v94
	v_add_f32_e32 v83, v95, v95
	v_mul_f32_e32 v82, 0x3fb8aa3b, v82
	v_mul_f32_e32 v83, 0x3fb8aa3b, v83
	v_exp_f32_e32 v82, v82
	v_exp_f32_e32 v83, v83
	v_sub_f32_e32 v82, 1.0, v82
	v_sub_f32_e32 v83, 1.0, v83
	v_max_f32_e32 v82, 0, v82
	v_max_f32_e32 v83, 0, v83
	v_sqrt_f32_e32 v82, v82
	v_sqrt_f32_e32 v83, v83
	s_waitcnt vmcnt(0)
	v_lshlrev_b32_e32 v96, 16, v92
	v_and_b32_e32 v97, 0xffff0000, v92
	v_pk_mul_f32 v[82:83], v[86:87], v[82:83]
	v_lshlrev_b32_e32 v92, 16, v93
	v_pk_mul_f32 v[86:87], v[82:83], v[96:97]
	v_add_f32_e32 v83, v88, v76
	v_mul_f32_e32 v83, 0xbfb8aa3b, v83
	v_exp_f32_e32 v83, v83
	v_add_f32_e32 v82, v84, v80
	v_mul_f32_e32 v82, 0xbfb8aa3b, v82
	v_exp_f32_e32 v82, v82
	v_add_f32_e32 v83, 1.0, v83
	v_rcp_f32_e32 v84, v83
	v_add_f32_e32 v83, v85, v81
	v_mul_f32_e32 v83, 0xbfb8aa3b, v83
	v_exp_f32_e32 v83, v83
	v_add_f32_e32 v82, 1.0, v82
	v_rcp_f32_e32 v82, v82
	v_add_f32_e32 v85, v89, v77
	v_add_f32_e32 v83, 1.0, v83
	v_rcp_f32_e32 v83, v83
	v_mul_f32_e32 v85, 0xbfb8aa3b, v85
	v_exp_f32_e32 v85, v85
	v_and_b32_e32 v93, 0xffff0000, v93
	v_pk_mul_f32 v[88:89], v[82:83], v[132:133]
	v_cvt_pk_bf16_f32 v86, v86, v87
	v_add_f32_e32 v82, v88, v88
	v_add_f32_e32 v83, v89, v89
	v_mul_f32_e32 v82, 0x3fb8aa3b, v82
	v_mul_f32_e32 v83, 0x3fb8aa3b, v83
	v_exp_f32_e32 v82, v82
	v_exp_f32_e32 v83, v83
	v_add_f32_e32 v85, 1.0, v85
	v_rcp_f32_e32 v85, v85
	v_sub_f32_e32 v82, 1.0, v82
	v_sub_f32_e32 v83, 1.0, v83
	v_max_f32_e32 v82, 0, v82
	v_max_f32_e32 v83, 0, v83
	v_sqrt_f32_e32 v82, v82
	v_sqrt_f32_e32 v83, v83
	s_nop 0
	v_pk_mul_f32 v[82:83], v[84:85], v[82:83]
	s_nop 0
	v_pk_mul_f32 v[84:85], v[82:83], v[92:93]
	v_cvt_pk_bf16_f32 v93, v88, v89
	v_mad_i64_i32 v[88:89], s[6:7], v90, s84, v[130:131]
	v_lshl_add_u64 v[88:89], v[88:89], 0, v[146:147]
	v_add_co_u32_e32 v88, vcc, s69, v88
	v_add_u32_e32 v82, 16, v90
	v_cvt_pk_bf16_f32 v92, v94, v95
	v_addc_co_u32_e32 v89, vcc, 0, v89, vcc
	v_cvt_pk_bf16_f32 v87, v84, v85
	global_store_dwordx2 v[88:89], v[92:93], off offset:2048
	global_store_dwordx2 v[88:89], v[86:87], off
	s_nop 0
	v_ashrrev_i32_e32 v83, 31, v82
	v_lshlrev_b64 v[84:85], 11, v[82:83]
	v_lshl_add_u64 v[84:85], s[14:15], 0, v[84:85]
	v_lshl_add_u64 v[84:85], v[84:85], 0, v[146:147]
	global_load_dwordx2 v[84:85], v[84:85], off
	v_mad_i64_i32 v[68:69], s[6:7], v82, s84, v[130:131]
	v_lshl_add_u64 v[68:69], v[68:69], 0, v[146:147]
	v_add_co_u32_e32 v68, vcc, s69, v68
	s_waitcnt vmcnt(0)
	v_lshlrev_b32_e32 v78, 16, v84
	v_and_b32_e32 v79, 0xffff0000, v84
	v_lshlrev_b32_e32 v76, 16, v85
	v_and_b32_e32 v77, 0xffff0000, v85
	v_pk_mul_f32 v[70:71], v[70:71], v[78:79]
	v_pk_mul_f32 v[72:73], v[72:73], v[76:77]
	v_addc_co_u32_e32 v69, vcc, 0, v69, vcc
	global_store_dwordx2 v[68:69], v[66:67], off offset:2048
	v_cvt_pk_bf16_f32 v66, v70, v71
	v_cvt_pk_bf16_f32 v67, v72, v73
	global_store_dwordx2 v[68:69], v[66:67], off
	global_load_dwordx4 v[70:73], v[152:153], off offset:16
	s_nop 0
	global_load_dwordx4 v[66:69], v[156:157], off offset:16
	global_load_dwordx4 v[76:79], v[154:155], off offset:16
	s_waitcnt vmcnt(0)
	v_add_f32_e32 v58, v58, v70
	v_ashrrev_i32_e32 v149, 31, v148
	v_max_f32_e64 v80, -v76, -v76
	v_mul_f32_e64 v76, |v76|, s72
	v_exp_f32_e32 v76, v76
	v_mul_f32_e32 v58, 0xbfb8aa3b, v58
	v_exp_f32_e32 v58, v58
	v_max_f32_e32 v80, 0, v80
	v_add_f32_e32 v76, 1.0, v76
	v_cmp_gt_f32_e32 vcc, s71, v76
	v_add_f32_e32 v58, 1.0, v58
	v_rcp_f32_e32 v86, v58
	v_cndmask_b32_e64 v81, 0, 32, vcc
	v_ldexp_f32 v76, v76, v81
	v_log_f32_e32 v76, v76
	v_add_f32_e32 v58, v62, v66
	v_mul_f32_e32 v58, 0xbfb8aa3b, v58
	v_exp_f32_e32 v58, v58
	v_mul_f32_e32 v81, 0x3f317217, v76
	v_fma_f32 v81, v76, s73, -v81
	v_fmac_f32_e32 v81, 0x3377d1cf, v76
	v_fmac_f32_e32 v81, 0x3f317217, v76
	v_cmp_lt_f32_e64 s[6:7], |v76|, s74
	v_add_f32_e32 v58, 1.0, v58
	v_rcp_f32_e32 v62, v58
	v_cndmask_b32_e64 v76, v76, v81, s[6:7]
	v_cndmask_b32_e32 v81, 0, v243, vcc
	v_sub_f32_e32 v82, v76, v81
	v_max_f32_e64 v76, -v77, -v77
	v_max_f32_e32 v81, 0, v76
	v_mul_f32_e64 v76, |v77|, s72
	v_exp_f32_e32 v76, v76
	v_add_f32_e32 v58, v59, v71
	v_mul_f32_e32 v58, 0xbfb8aa3b, v58
	v_exp_f32_e32 v58, v58
	v_add_f32_e32 v76, 1.0, v76
	v_cmp_gt_f32_e32 vcc, s71, v76
	v_add_f32_e32 v60, v60, v72
	v_add_f32_e32 v58, 1.0, v58
	v_cndmask_b32_e64 v77, 0, 32, vcc
	v_ldexp_f32 v76, v76, v77
	v_log_f32_e32 v76, v76
	v_rcp_f32_e32 v87, v58
	v_add_f32_e32 v58, v63, v67
	v_mul_f32_e32 v58, 0xbfb8aa3b, v58
	v_mul_f32_e32 v77, 0x3f317217, v76
	v_fma_f32 v77, v76, s73, -v77
	v_fmac_f32_e32 v77, 0x3377d1cf, v76
	v_fmac_f32_e32 v77, 0x3f317217, v76
	v_cmp_lt_f32_e64 s[6:7], |v76|, s74
	v_exp_f32_e32 v58, v58
	v_mul_f32_e32 v60, 0xbfb8aa3b, v60
	v_cndmask_b32_e64 v76, v76, v77, s[6:7]
	v_cndmask_b32_e32 v77, 0, v243, vcc
	v_sub_f32_e32 v83, v76, v77
	v_mul_f32_e64 v77, |v78|, s72
	v_exp_f32_e32 v77, v77
	v_max_f32_e64 v76, -v78, -v78
	v_add_f32_e32 v58, 1.0, v58
	v_rcp_f32_e32 v63, v58
	v_add_f32_e32 v77, 1.0, v77
	v_cmp_gt_f32_e32 vcc, s71, v77
	v_pk_add_f32 v[58:59], v[80:81], v[82:83]
	v_exp_f32_e32 v60, v60
	v_cndmask_b32_e64 v78, 0, 32, vcc
	v_ldexp_f32 v77, v77, v78
	v_log_f32_e32 v77, v77
	v_pk_mul_f32 v[58:59], v[58:59], s[2:3] op_sel_hi:[1,0]
	v_add_f32_e32 v60, 1.0, v60
	v_pk_mul_f32 v[80:81], v[86:87], v[58:59]
	v_mul_f32_e32 v78, 0x3f317217, v77
	v_fma_f32 v78, v77, s73, -v78
	v_fmac_f32_e32 v78, 0x3377d1cf, v77
	v_fmac_f32_e32 v78, 0x3f317217, v77
	v_cmp_lt_f32_e64 s[6:7], |v77|, s74
	v_add_f32_e32 v82, v80, v80
	v_add_f32_e32 v83, v81, v81
	v_cndmask_b32_e64 v77, v77, v78, s[6:7]
	v_cndmask_b32_e32 v78, 0, v243, vcc
	v_sub_f32_e32 v78, v77, v78
	v_max_f32_e64 v77, -v79, -v79
	v_mul_f32_e64 v79, |v79|, s72
	v_exp_f32_e32 v79, v79
	v_mul_f32_e32 v82, 0x3fb8aa3b, v82
	v_mul_f32_e32 v83, 0x3fb8aa3b, v83
	v_exp_f32_e32 v82, v82
	v_add_f32_e32 v79, 1.0, v79
	v_cmp_gt_f32_e32 vcc, s71, v79
	v_exp_f32_e32 v83, v83
	v_sub_f32_e32 v82, 1.0, v82
	v_cndmask_b32_e64 v84, 0, 32, vcc
	v_ldexp_f32 v79, v79, v84
	v_log_f32_e32 v79, v79
	v_sub_f32_e32 v83, 1.0, v83
	v_max_f32_e32 v82, 0, v82
	v_max_f32_e32 v83, 0, v83
	v_mul_f32_e32 v84, 0x3f317217, v79
	v_fma_f32 v84, v79, s73, -v84
	v_fmac_f32_e32 v84, 0x3377d1cf, v79
	v_fmac_f32_e32 v84, 0x3f317217, v79
	v_cmp_lt_f32_e64 s[6:7], |v79|, s74
	v_sqrt_f32_e32 v82, v82
	v_sqrt_f32_e32 v83, v83
	v_cndmask_b32_e64 v79, v79, v84, s[6:7]
	v_cndmask_b32_e32 v84, 0, v243, vcc
	v_sub_f32_e32 v79, v79, v84
	v_lshlrev_b64 v[84:85], 11, v[148:149]
	v_lshl_add_u64 v[84:85], s[14:15], 0, v[84:85]
	v_lshl_add_u64 v[84:85], v[84:85], 0, v[146:147]
	global_load_dwordx2 v[84:85], v[84:85], off offset:8
	v_pk_mul_f32 v[62:63], v[62:63], v[82:83]
	v_max_f32_e32 v76, 0, v76
	v_max_f32_e32 v77, 0, v77
	v_add_f32_e32 v50, v50, v70
	v_add_f32_e32 v51, v51, v71
	v_mul_f32_e32 v50, 0xbfb8aa3b, v50
	v_mul_f32_e32 v51, 0xbfb8aa3b, v51
	v_exp_f32_e32 v50, v50
	v_exp_f32_e32 v51, v51
	v_add_f32_e32 v54, v54, v66
	v_add_f32_e32 v55, v55, v67
	v_add_f32_e32 v50, 1.0, v50
	v_add_f32_e32 v51, 1.0, v51
	v_rcp_f32_e32 v50, v50
	v_rcp_f32_e32 v51, v51
	v_mul_f32_e32 v54, 0xbfb8aa3b, v54
	v_mul_f32_e32 v55, 0xbfb8aa3b, v55
	v_exp_f32_e32 v54, v54
	v_exp_f32_e32 v55, v55
	v_add_f32_e32 v42, v42, v70
	v_add_f32_e32 v43, v43, v71
	v_add_f32_e32 v54, 1.0, v54
	v_add_f32_e32 v55, 1.0, v55
	v_rcp_f32_e32 v54, v54
	v_rcp_f32_e32 v55, v55
	v_mul_f32_e32 v42, 0xbfb8aa3b, v42
	v_mul_f32_e32 v43, 0xbfb8aa3b, v43
	v_exp_f32_e32 v42, v42
	v_exp_f32_e32 v43, v43
	v_add_f32_e32 v46, v46, v66
	v_add_f32_e32 v47, v47, v67
	v_add_f32_e32 v42, 1.0, v42
	v_add_f32_e32 v43, 1.0, v43
	v_rcp_f32_e32 v42, v42
	v_rcp_f32_e32 v43, v43
	v_mul_f32_e32 v46, 0xbfb8aa3b, v46
	v_mul_f32_e32 v47, 0xbfb8aa3b, v47
	v_exp_f32_e32 v46, v46
	v_exp_f32_e32 v47, v47
	v_add_f32_e32 v34, v34, v70
	v_add_f32_e32 v35, v35, v71
	v_add_f32_e32 v46, 1.0, v46
	v_add_f32_e32 v47, 1.0, v47
	v_rcp_f32_e32 v46, v46
	v_rcp_f32_e32 v47, v47
	v_mul_f32_e32 v34, 0xbfb8aa3b, v34
	v_mul_f32_e32 v35, 0xbfb8aa3b, v35
	v_exp_f32_e32 v34, v34
	v_exp_f32_e32 v35, v35
	v_add_f32_e32 v38, v38, v66
	v_add_f32_e32 v39, v39, v67
	v_add_f32_e32 v34, 1.0, v34
	v_add_f32_e32 v35, 1.0, v35
	v_rcp_f32_e32 v34, v34
	v_rcp_f32_e32 v35, v35
	v_mul_f32_e32 v38, 0xbfb8aa3b, v38
	v_mul_f32_e32 v39, 0xbfb8aa3b, v39
	v_exp_f32_e32 v38, v38
	v_exp_f32_e32 v39, v39
	v_add_f32_e32 v26, v26, v70
	v_add_f32_e32 v27, v27, v71
	v_add_f32_e32 v38, 1.0, v38
	v_add_f32_e32 v39, 1.0, v39
	v_rcp_f32_e32 v38, v38
	v_rcp_f32_e32 v39, v39
	v_mul_f32_e32 v26, 0xbfb8aa3b, v26
	v_mul_f32_e32 v27, 0xbfb8aa3b, v27
	v_exp_f32_e32 v26, v26
	v_exp_f32_e32 v27, v27
	v_add_f32_e32 v30, v30, v66
	v_add_f32_e32 v31, v31, v67
	v_add_f32_e32 v26, 1.0, v26
	v_add_f32_e32 v27, 1.0, v27
	v_rcp_f32_e32 v26, v26
	v_rcp_f32_e32 v27, v27
	v_mul_f32_e32 v30, 0xbfb8aa3b, v30
	v_mul_f32_e32 v31, 0xbfb8aa3b, v31
	v_exp_f32_e32 v30, v30
	v_exp_f32_e32 v31, v31
	s_waitcnt vmcnt(0)
	v_lshlrev_b32_e32 v86, 16, v84
	v_and_b32_e32 v87, 0xffff0000, v84
	v_pk_mul_f32 v[82:83], v[62:63], v[86:87]
	v_rcp_f32_e32 v62, v60
	v_add_f32_e32 v60, v64, v68
	v_mul_f32_e32 v60, 0xbfb8aa3b, v60
	v_exp_f32_e32 v60, v60
	v_add_f32_e32 v30, 1.0, v30
	v_add_f32_e32 v31, 1.0, v31
	v_rcp_f32_e32 v30, v30
	v_add_f32_e32 v60, 1.0, v60
	v_rcp_f32_e32 v64, v60
	v_add_f32_e32 v60, v61, v73
	v_mul_f32_e32 v60, 0xbfb8aa3b, v60
	v_exp_f32_e32 v60, v60
	v_rcp_f32_e32 v31, v31
	v_add_f32_e32 v18, v18, v70
	v_add_f32_e32 v19, v19, v71
	v_add_f32_e32 v60, 1.0, v60
	v_rcp_f32_e32 v63, v60
	v_add_f32_e32 v60, v65, v69
	v_mul_f32_e32 v60, 0xbfb8aa3b, v60
	v_exp_f32_e32 v60, v60
	v_mul_f32_e32 v18, 0xbfb8aa3b, v18
	v_mul_f32_e32 v19, 0xbfb8aa3b, v19
	v_exp_f32_e32 v18, v18
	v_add_f32_e32 v60, 1.0, v60
	v_rcp_f32_e32 v65, v60
	v_pk_add_f32 v[60:61], v[76:77], v[78:79]
	v_lshlrev_b32_e32 v78, 16, v85
	v_pk_mul_f32 v[60:61], v[60:61], s[2:3] op_sel_hi:[1,0]
	v_and_b32_e32 v79, 0xffff0000, v85
	v_pk_mul_f32 v[62:63], v[62:63], v[60:61]
	v_exp_f32_e32 v19, v19
	v_add_f32_e32 v76, v62, v62
	v_add_f32_e32 v77, v63, v63
	v_mul_f32_e32 v76, 0x3fb8aa3b, v76
	v_mul_f32_e32 v77, 0x3fb8aa3b, v77
	v_exp_f32_e32 v76, v76
	v_exp_f32_e32 v77, v77
	v_add_f32_e32 v18, 1.0, v18
	v_add_f32_e32 v19, 1.0, v19
	v_sub_f32_e32 v76, 1.0, v76
	v_sub_f32_e32 v77, 1.0, v77
	v_max_f32_e32 v76, 0, v76
	v_max_f32_e32 v77, 0, v77
	v_sqrt_f32_e32 v76, v76
	v_sqrt_f32_e32 v77, v77
	v_rcp_f32_e32 v18, v18
	v_rcp_f32_e32 v19, v19
	v_add_f32_e32 v22, v22, v66
	v_pk_mul_f32 v[64:65], v[64:65], v[76:77]
	v_add_f32_e32 v23, v23, v67
	v_pk_mul_f32 v[76:77], v[64:65], v[78:79]
	v_cvt_pk_bf16_f32 v78, v80, v81
	v_cvt_pk_bf16_f32 v79, v62, v63
	v_mad_i64_i32 v[80:81], s[6:7], v148, s84, v[130:131]
	v_lshlrev_b64 v[62:63], 1, v[74:75]
	v_lshl_add_u64 v[74:75], v[80:81], 0, v[62:63]
	v_add_co_u32_e32 v74, vcc, s69, v74
	v_add_u32_e32 v64, 16, v148
	s_nop 0
	v_addc_co_u32_e32 v75, vcc, 0, v75, vcc
	global_store_dwordx2 v[74:75], v[78:79], off offset:2048
	v_cvt_pk_bf16_f32 v78, v82, v83
	v_cvt_pk_bf16_f32 v79, v76, v77
	global_store_dwordx2 v[74:75], v[78:79], off
	v_pk_mul_f32 v[76:77], v[50:51], v[58:59]
	v_ashrrev_i32_e32 v65, 31, v64
	v_lshlrev_b64 v[74:75], 11, v[64:65]
	v_lshl_add_u64 v[74:75], s[14:15], 0, v[74:75]
	v_lshl_add_u64 v[74:75], v[74:75], 0, v[146:147]
	global_load_dwordx2 v[74:75], v[74:75], off offset:8
	v_add_f32_e32 v50, v76, v76
	v_add_f32_e32 v51, v77, v77
	v_mul_f32_e32 v50, 0x3fb8aa3b, v50
	v_mul_f32_e32 v51, 0x3fb8aa3b, v51
	v_exp_f32_e32 v50, v50
	v_exp_f32_e32 v51, v51
	v_mul_f32_e32 v22, 0xbfb8aa3b, v22
	v_mul_f32_e32 v23, 0xbfb8aa3b, v23
	v_sub_f32_e32 v50, 1.0, v50
	v_sub_f32_e32 v51, 1.0, v51
	v_max_f32_e32 v50, 0, v50
	v_max_f32_e32 v51, 0, v51
	v_sqrt_f32_e32 v50, v50
	v_sqrt_f32_e32 v51, v51
	v_exp_f32_e32 v22, v22
	v_exp_f32_e32 v23, v23
	v_add_f32_e32 v10, v10, v70
	v_pk_mul_f32 v[50:51], v[54:55], v[50:51]
	v_add_f32_e32 v22, 1.0, v22
	v_add_f32_e32 v23, 1.0, v23
	v_rcp_f32_e32 v22, v22
	v_rcp_f32_e32 v23, v23
	v_add_f32_e32 v11, v11, v71
	v_mul_f32_e32 v10, 0xbfb8aa3b, v10
	v_mul_f32_e32 v11, 0xbfb8aa3b, v11
	v_exp_f32_e32 v10, v10
	v_exp_f32_e32 v11, v11
	v_add_f32_e32 v14, v14, v66
	v_add_f32_e32 v15, v15, v67
	v_add_f32_e32 v10, 1.0, v10
	v_add_f32_e32 v11, 1.0, v11
	v_rcp_f32_e32 v10, v10
	v_rcp_f32_e32 v11, v11
	v_mul_f32_e32 v14, 0xbfb8aa3b, v14
	v_mul_f32_e32 v15, 0xbfb8aa3b, v15
	v_exp_f32_e32 v14, v14
	v_exp_f32_e32 v15, v15
	v_add_f32_e32 v2, v2, v70
	v_add_f32_e32 v3, v3, v71
	v_add_f32_e32 v14, 1.0, v14
	v_add_f32_e32 v15, 1.0, v15
	v_rcp_f32_e32 v14, v14
	v_rcp_f32_e32 v15, v15
	v_mul_f32_e32 v2, 0xbfb8aa3b, v2
	v_mul_f32_e32 v3, 0xbfb8aa3b, v3
	v_exp_f32_e32 v2, v2
	v_exp_f32_e32 v3, v3
	v_add_f32_e32 v4, v4, v72
	v_add_f32_e32 v5, v5, v73
	v_add_f32_e32 v2, 1.0, v2
	v_add_f32_e32 v3, 1.0, v3
	v_rcp_f32_e32 v2, v2
	v_rcp_f32_e32 v3, v3
	v_mul_f32_e32 v4, 0xbfb8aa3b, v4
	v_mul_f32_e32 v5, 0xbfb8aa3b, v5
	v_exp_f32_e32 v4, v4
	v_pk_mul_f32 v[2:3], v[2:3], v[58:59]
	v_exp_f32_e32 v5, v5
	v_add_f32_e32 v6, v6, v66
	v_add_f32_e32 v4, 1.0, v4
	v_rcp_f32_e32 v4, v4
	v_add_f32_e32 v5, 1.0, v5
	v_rcp_f32_e32 v5, v5
	v_add_f32_e32 v7, v7, v67
	v_mul_f32_e32 v6, 0xbfb8aa3b, v6
	v_mul_f32_e32 v7, 0xbfb8aa3b, v7
	v_exp_f32_e32 v6, v6
	v_exp_f32_e32 v7, v7
	v_pk_mul_f32 v[4:5], v[4:5], v[60:61]
	v_add_f32_e32 v8, v8, v68
	v_add_f32_e32 v6, 1.0, v6
	v_add_f32_e32 v7, 1.0, v7
	v_rcp_f32_e32 v6, v6
	v_rcp_f32_e32 v7, v7
	v_add_f32_e32 v9, v9, v69
	v_mul_f32_e32 v8, 0xbfb8aa3b, v8
	v_mul_f32_e32 v9, 0xbfb8aa3b, v9
	v_exp_f32_e32 v8, v8
	v_exp_f32_e32 v9, v9
	s_waitcnt vmcnt(0)
	v_lshlrev_b32_e32 v78, 16, v74
	v_and_b32_e32 v79, 0xffff0000, v74
	v_pk_mul_f32 v[54:55], v[50:51], v[78:79]
	v_add_f32_e32 v51, v56, v68
	v_mul_f32_e32 v51, 0xbfb8aa3b, v51
	v_exp_f32_e32 v51, v51
	v_add_f32_e32 v50, v52, v72
	v_mul_f32_e32 v50, 0xbfb8aa3b, v50
	v_exp_f32_e32 v50, v50
	v_add_f32_e32 v51, 1.0, v51
	v_rcp_f32_e32 v52, v51
	v_add_f32_e32 v51, v53, v73
	v_mul_f32_e32 v51, 0xbfb8aa3b, v51
	v_exp_f32_e32 v51, v51
	v_add_f32_e32 v50, 1.0, v50
	v_rcp_f32_e32 v50, v50
	v_add_f32_e32 v53, v57, v69
	v_add_f32_e32 v51, 1.0, v51
	v_rcp_f32_e32 v51, v51
	v_mul_f32_e32 v53, 0xbfb8aa3b, v53
	v_exp_f32_e32 v53, v53
	v_lshlrev_b32_e32 v74, 16, v75
	v_pk_mul_f32 v[56:57], v[50:51], v[60:61]
	v_and_b32_e32 v75, 0xffff0000, v75
	v_add_f32_e32 v50, v56, v56
	v_add_f32_e32 v51, v57, v57
	v_mul_f32_e32 v50, 0x3fb8aa3b, v50
	v_mul_f32_e32 v51, 0x3fb8aa3b, v51
	v_exp_f32_e32 v50, v50
	v_exp_f32_e32 v51, v51
	v_add_f32_e32 v53, 1.0, v53
	v_rcp_f32_e32 v53, v53
	v_sub_f32_e32 v50, 1.0, v50
	v_sub_f32_e32 v51, 1.0, v51
	v_max_f32_e32 v50, 0, v50
	v_max_f32_e32 v51, 0, v51
	v_sqrt_f32_e32 v50, v50
	v_sqrt_f32_e32 v51, v51
	v_cvt_pk_bf16_f32 v54, v54, v55
	v_add_f32_e32 v8, 1.0, v8
	v_add_f32_e32 v9, 1.0, v9
	v_pk_mul_f32 v[50:51], v[52:53], v[50:51]
	v_rcp_f32_e32 v8, v8
	v_pk_mul_f32 v[52:53], v[50:51], v[74:75]
	v_cvt_pk_bf16_f32 v75, v56, v57
	v_mad_i64_i32 v[56:57], s[6:7], v64, s84, v[130:131]
	v_lshl_add_u64 v[56:57], v[56:57], 0, v[62:63]
	v_add_co_u32_e32 v56, vcc, s69, v56
	v_add_u32_e32 v50, 16, v64
	v_cvt_pk_bf16_f32 v74, v76, v77
	v_addc_co_u32_e32 v57, vcc, 0, v57, vcc
	v_cvt_pk_bf16_f32 v55, v52, v53
	global_store_dwordx2 v[56:57], v[74:75], off offset:2048
	global_store_dwordx2 v[56:57], v[54:55], off
	v_pk_mul_f32 v[54:55], v[42:43], v[58:59]
	v_ashrrev_i32_e32 v51, 31, v50
	v_lshlrev_b64 v[52:53], 11, v[50:51]
	v_lshl_add_u64 v[52:53], s[14:15], 0, v[52:53]
	v_lshl_add_u64 v[52:53], v[52:53], 0, v[146:147]
	global_load_dwordx2 v[52:53], v[52:53], off offset:8
	v_add_f32_e32 v42, v54, v54
	v_add_f32_e32 v43, v55, v55
	v_mul_f32_e32 v42, 0x3fb8aa3b, v42
	v_mul_f32_e32 v43, 0x3fb8aa3b, v43
	v_exp_f32_e32 v42, v42
	v_exp_f32_e32 v43, v43
	v_rcp_f32_e32 v9, v9
	s_mov_b32 s2, s22
	v_sub_f32_e32 v42, 1.0, v42
	v_sub_f32_e32 v43, 1.0, v43
	v_max_f32_e32 v42, 0, v42
	v_max_f32_e32 v43, 0, v43
	v_sqrt_f32_e32 v42, v42
	v_sqrt_f32_e32 v43, v43
	s_waitcnt vmcnt(0)
	v_lshlrev_b32_e32 v56, 16, v52
	v_and_b32_e32 v57, 0xffff0000, v52
	v_pk_mul_f32 v[42:43], v[46:47], v[42:43]
	v_lshlrev_b32_e32 v52, 16, v53
	v_pk_mul_f32 v[46:47], v[42:43], v[56:57]
	v_add_f32_e32 v43, v48, v68
	v_mul_f32_e32 v43, 0xbfb8aa3b, v43
	v_exp_f32_e32 v43, v43
	v_add_f32_e32 v42, v44, v72
	v_mul_f32_e32 v42, 0xbfb8aa3b, v42
	v_exp_f32_e32 v42, v42
	v_add_f32_e32 v43, 1.0, v43
	v_rcp_f32_e32 v44, v43
	v_add_f32_e32 v43, v45, v73
	v_mul_f32_e32 v43, 0xbfb8aa3b, v43
	v_exp_f32_e32 v43, v43
	v_add_f32_e32 v42, 1.0, v42
	v_rcp_f32_e32 v42, v42
	v_add_f32_e32 v45, v49, v69
	v_add_f32_e32 v43, 1.0, v43
	v_rcp_f32_e32 v43, v43
	v_mul_f32_e32 v45, 0xbfb8aa3b, v45
	v_exp_f32_e32 v45, v45
	v_and_b32_e32 v53, 0xffff0000, v53
	v_pk_mul_f32 v[48:49], v[42:43], v[60:61]
	v_cvt_pk_bf16_f32 v46, v46, v47
	v_add_f32_e32 v42, v48, v48
	v_add_f32_e32 v43, v49, v49
	v_mul_f32_e32 v42, 0x3fb8aa3b, v42
	v_mul_f32_e32 v43, 0x3fb8aa3b, v43
	v_exp_f32_e32 v42, v42
	v_exp_f32_e32 v43, v43
	v_add_f32_e32 v45, 1.0, v45
	v_rcp_f32_e32 v45, v45
	v_sub_f32_e32 v42, 1.0, v42
	v_sub_f32_e32 v43, 1.0, v43
	v_max_f32_e32 v42, 0, v42
	v_max_f32_e32 v43, 0, v43
	v_sqrt_f32_e32 v42, v42
	v_sqrt_f32_e32 v43, v43
	s_nop 0
	v_pk_mul_f32 v[42:43], v[44:45], v[42:43]
	s_nop 0
	v_pk_mul_f32 v[44:45], v[42:43], v[52:53]
	v_cvt_pk_bf16_f32 v53, v48, v49
	v_mad_i64_i32 v[48:49], s[6:7], v50, s84, v[130:131]
	v_lshl_add_u64 v[48:49], v[48:49], 0, v[62:63]
	v_add_co_u32_e32 v48, vcc, s69, v48
	v_add_u32_e32 v42, 16, v50
	v_cvt_pk_bf16_f32 v52, v54, v55
	v_addc_co_u32_e32 v49, vcc, 0, v49, vcc
	v_cvt_pk_bf16_f32 v47, v44, v45
	global_store_dwordx2 v[48:49], v[52:53], off offset:2048
	global_store_dwordx2 v[48:49], v[46:47], off
	v_pk_mul_f32 v[46:47], v[34:35], v[58:59]
	v_ashrrev_i32_e32 v43, 31, v42
	v_lshlrev_b64 v[44:45], 11, v[42:43]
	v_lshl_add_u64 v[44:45], s[14:15], 0, v[44:45]
	v_lshl_add_u64 v[44:45], v[44:45], 0, v[146:147]
	global_load_dwordx2 v[44:45], v[44:45], off offset:8
	v_add_f32_e32 v34, v46, v46
	v_add_f32_e32 v35, v47, v47
	v_mul_f32_e32 v34, 0x3fb8aa3b, v34
	v_mul_f32_e32 v35, 0x3fb8aa3b, v35
	v_exp_f32_e32 v34, v34
	v_exp_f32_e32 v35, v35
	v_sub_f32_e32 v34, 1.0, v34
	v_sub_f32_e32 v35, 1.0, v35
	v_max_f32_e32 v34, 0, v34
	v_max_f32_e32 v35, 0, v35
	v_sqrt_f32_e32 v34, v34
	v_sqrt_f32_e32 v35, v35
	s_waitcnt vmcnt(0)
	v_lshlrev_b32_e32 v48, 16, v44
	v_and_b32_e32 v49, 0xffff0000, v44
	v_pk_mul_f32 v[34:35], v[38:39], v[34:35]
	v_lshlrev_b32_e32 v44, 16, v45
	v_pk_mul_f32 v[38:39], v[34:35], v[48:49]
	v_add_f32_e32 v35, v40, v68
	v_mul_f32_e32 v35, 0xbfb8aa3b, v35
	v_exp_f32_e32 v35, v35
	v_add_f32_e32 v34, v36, v72
	v_mul_f32_e32 v34, 0xbfb8aa3b, v34
	v_exp_f32_e32 v34, v34
	v_add_f32_e32 v35, 1.0, v35
	v_rcp_f32_e32 v36, v35
	v_add_f32_e32 v35, v37, v73
	v_mul_f32_e32 v35, 0xbfb8aa3b, v35
	v_exp_f32_e32 v35, v35
	v_add_f32_e32 v34, 1.0, v34
	v_rcp_f32_e32 v34, v34
	v_add_f32_e32 v37, v41, v69
	v_add_f32_e32 v35, 1.0, v35
	v_rcp_f32_e32 v35, v35
	v_mul_f32_e32 v37, 0xbfb8aa3b, v37
	v_exp_f32_e32 v37, v37
	v_and_b32_e32 v45, 0xffff0000, v45
	v_pk_mul_f32 v[40:41], v[34:35], v[60:61]
	v_cvt_pk_bf16_f32 v38, v38, v39
	v_add_f32_e32 v34, v40, v40
	v_add_f32_e32 v35, v41, v41
	v_mul_f32_e32 v34, 0x3fb8aa3b, v34
	v_mul_f32_e32 v35, 0x3fb8aa3b, v35
	v_exp_f32_e32 v34, v34
	v_exp_f32_e32 v35, v35
	v_add_f32_e32 v37, 1.0, v37
	v_rcp_f32_e32 v37, v37
	v_sub_f32_e32 v34, 1.0, v34
	v_sub_f32_e32 v35, 1.0, v35
	v_max_f32_e32 v34, 0, v34
	v_max_f32_e32 v35, 0, v35
	v_sqrt_f32_e32 v34, v34
	v_sqrt_f32_e32 v35, v35
	s_nop 0
	v_pk_mul_f32 v[34:35], v[36:37], v[34:35]
	s_nop 0
	v_pk_mul_f32 v[36:37], v[34:35], v[44:45]
	v_cvt_pk_bf16_f32 v45, v40, v41
	v_mad_i64_i32 v[40:41], s[6:7], v42, s84, v[130:131]
	v_lshl_add_u64 v[40:41], v[40:41], 0, v[62:63]
	v_add_co_u32_e32 v40, vcc, s69, v40
	v_add_u32_e32 v34, 0x50, v42
	v_cvt_pk_bf16_f32 v44, v46, v47
	v_addc_co_u32_e32 v41, vcc, 0, v41, vcc
	v_cvt_pk_bf16_f32 v39, v36, v37
	global_store_dwordx2 v[40:41], v[44:45], off offset:2048
	global_store_dwordx2 v[40:41], v[38:39], off
	v_pk_mul_f32 v[38:39], v[26:27], v[58:59]
	v_ashrrev_i32_e32 v35, 31, v34
	v_lshlrev_b64 v[36:37], 11, v[34:35]
	v_lshl_add_u64 v[36:37], s[14:15], 0, v[36:37]
	v_lshl_add_u64 v[36:37], v[36:37], 0, v[146:147]
	global_load_dwordx2 v[36:37], v[36:37], off offset:8
	v_add_f32_e32 v26, v38, v38
	v_add_f32_e32 v27, v39, v39
	v_mul_f32_e32 v26, 0x3fb8aa3b, v26
	v_mul_f32_e32 v27, 0x3fb8aa3b, v27
	v_exp_f32_e32 v26, v26
	v_exp_f32_e32 v27, v27
	v_sub_f32_e32 v26, 1.0, v26
	v_sub_f32_e32 v27, 1.0, v27
	v_max_f32_e32 v26, 0, v26
	v_max_f32_e32 v27, 0, v27
	v_sqrt_f32_e32 v26, v26
	v_sqrt_f32_e32 v27, v27
	s_waitcnt vmcnt(0)
	v_lshlrev_b32_e32 v40, 16, v36
	v_and_b32_e32 v41, 0xffff0000, v36
	v_pk_mul_f32 v[26:27], v[30:31], v[26:27]
	v_lshlrev_b32_e32 v36, 16, v37
	v_pk_mul_f32 v[30:31], v[26:27], v[40:41]
	v_add_f32_e32 v27, v32, v68
	v_mul_f32_e32 v27, 0xbfb8aa3b, v27
	v_exp_f32_e32 v27, v27
	v_add_f32_e32 v26, v28, v72
	v_mul_f32_e32 v26, 0xbfb8aa3b, v26
	v_exp_f32_e32 v26, v26
	v_add_f32_e32 v27, 1.0, v27
	v_rcp_f32_e32 v28, v27
	v_add_f32_e32 v27, v29, v73
	v_mul_f32_e32 v27, 0xbfb8aa3b, v27
	v_exp_f32_e32 v27, v27
	v_add_f32_e32 v26, 1.0, v26
	v_rcp_f32_e32 v26, v26
	v_add_f32_e32 v29, v33, v69
	v_add_f32_e32 v27, 1.0, v27
	v_rcp_f32_e32 v27, v27
	v_mul_f32_e32 v29, 0xbfb8aa3b, v29
	v_exp_f32_e32 v29, v29
	v_and_b32_e32 v37, 0xffff0000, v37
	v_pk_mul_f32 v[32:33], v[26:27], v[60:61]
	v_cvt_pk_bf16_f32 v30, v30, v31
	v_add_f32_e32 v26, v32, v32
	v_add_f32_e32 v27, v33, v33
	v_mul_f32_e32 v26, 0x3fb8aa3b, v26
	v_mul_f32_e32 v27, 0x3fb8aa3b, v27
	v_exp_f32_e32 v26, v26
	v_exp_f32_e32 v27, v27
	v_add_f32_e32 v29, 1.0, v29
	v_rcp_f32_e32 v29, v29
	v_sub_f32_e32 v26, 1.0, v26
	v_sub_f32_e32 v27, 1.0, v27
	v_max_f32_e32 v26, 0, v26
	v_max_f32_e32 v27, 0, v27
	v_sqrt_f32_e32 v26, v26
	v_sqrt_f32_e32 v27, v27
	s_nop 0
	v_pk_mul_f32 v[26:27], v[28:29], v[26:27]
	s_nop 0
	v_pk_mul_f32 v[28:29], v[26:27], v[36:37]
	v_cvt_pk_bf16_f32 v37, v32, v33
	v_mad_i64_i32 v[32:33], s[6:7], v34, s84, v[130:131]
	v_lshl_add_u64 v[32:33], v[32:33], 0, v[62:63]
	v_add_co_u32_e32 v32, vcc, s69, v32
	v_add_u32_e32 v26, 16, v34
	v_cvt_pk_bf16_f32 v36, v38, v39
	v_addc_co_u32_e32 v33, vcc, 0, v33, vcc
	v_cvt_pk_bf16_f32 v31, v28, v29
	global_store_dwordx2 v[32:33], v[36:37], off offset:2048
	global_store_dwordx2 v[32:33], v[30:31], off
	v_pk_mul_f32 v[30:31], v[18:19], v[58:59]
	v_ashrrev_i32_e32 v27, 31, v26
	v_lshlrev_b64 v[28:29], 11, v[26:27]
	v_lshl_add_u64 v[28:29], s[14:15], 0, v[28:29]
	v_lshl_add_u64 v[28:29], v[28:29], 0, v[146:147]
	global_load_dwordx2 v[28:29], v[28:29], off offset:8
	v_add_f32_e32 v18, v30, v30
	v_add_f32_e32 v19, v31, v31
	v_mul_f32_e32 v18, 0x3fb8aa3b, v18
	v_mul_f32_e32 v19, 0x3fb8aa3b, v19
	v_exp_f32_e32 v18, v18
	v_exp_f32_e32 v19, v19
	v_sub_f32_e32 v18, 1.0, v18
	v_sub_f32_e32 v19, 1.0, v19
	v_max_f32_e32 v18, 0, v18
	v_max_f32_e32 v19, 0, v19
	v_sqrt_f32_e32 v18, v18
	v_sqrt_f32_e32 v19, v19
	s_waitcnt vmcnt(0)
	v_lshlrev_b32_e32 v32, 16, v28
	v_and_b32_e32 v33, 0xffff0000, v28
	v_pk_mul_f32 v[18:19], v[22:23], v[18:19]
	v_lshlrev_b32_e32 v28, 16, v29
	v_pk_mul_f32 v[22:23], v[18:19], v[32:33]
	v_add_f32_e32 v19, v24, v68
	v_mul_f32_e32 v19, 0xbfb8aa3b, v19
	v_exp_f32_e32 v19, v19
	v_add_f32_e32 v18, v20, v72
	v_mul_f32_e32 v18, 0xbfb8aa3b, v18
	v_exp_f32_e32 v18, v18
	v_add_f32_e32 v19, 1.0, v19
	v_rcp_f32_e32 v20, v19
	v_add_f32_e32 v19, v21, v73
	v_mul_f32_e32 v19, 0xbfb8aa3b, v19
	v_exp_f32_e32 v19, v19
	v_add_f32_e32 v18, 1.0, v18
	v_rcp_f32_e32 v18, v18
	v_add_f32_e32 v21, v25, v69
	v_add_f32_e32 v19, 1.0, v19
	v_rcp_f32_e32 v19, v19
	v_mul_f32_e32 v21, 0xbfb8aa3b, v21
	v_exp_f32_e32 v21, v21
	v_and_b32_e32 v29, 0xffff0000, v29
	v_pk_mul_f32 v[24:25], v[18:19], v[60:61]
	v_cvt_pk_bf16_f32 v22, v22, v23
	v_add_f32_e32 v18, v24, v24
	v_add_f32_e32 v19, v25, v25
	v_mul_f32_e32 v18, 0x3fb8aa3b, v18
	v_mul_f32_e32 v19, 0x3fb8aa3b, v19
	v_exp_f32_e32 v18, v18
	v_exp_f32_e32 v19, v19
	v_add_f32_e32 v21, 1.0, v21
	v_rcp_f32_e32 v21, v21
	v_sub_f32_e32 v18, 1.0, v18
	v_sub_f32_e32 v19, 1.0, v19
	v_max_f32_e32 v18, 0, v18
	v_max_f32_e32 v19, 0, v19
	v_sqrt_f32_e32 v18, v18
	v_sqrt_f32_e32 v19, v19
	s_nop 0
	v_pk_mul_f32 v[18:19], v[20:21], v[18:19]
	s_nop 0
	v_pk_mul_f32 v[20:21], v[18:19], v[28:29]
	v_cvt_pk_bf16_f32 v29, v24, v25
	v_mad_i64_i32 v[24:25], s[6:7], v26, s84, v[130:131]
	v_lshl_add_u64 v[24:25], v[24:25], 0, v[62:63]
	v_add_co_u32_e32 v24, vcc, s69, v24
	v_add_u32_e32 v18, 16, v26
	v_cvt_pk_bf16_f32 v28, v30, v31
	v_addc_co_u32_e32 v25, vcc, 0, v25, vcc
	v_cvt_pk_bf16_f32 v23, v20, v21
	global_store_dwordx2 v[24:25], v[28:29], off offset:2048
	global_store_dwordx2 v[24:25], v[22:23], off
	v_pk_mul_f32 v[22:23], v[10:11], v[58:59]
	v_ashrrev_i32_e32 v19, 31, v18
	v_lshlrev_b64 v[20:21], 11, v[18:19]
	v_lshl_add_u64 v[20:21], s[14:15], 0, v[20:21]
	v_lshl_add_u64 v[20:21], v[20:21], 0, v[146:147]
	global_load_dwordx2 v[20:21], v[20:21], off offset:8
	v_add_f32_e32 v10, v22, v22
	v_add_f32_e32 v11, v23, v23
	v_mul_f32_e32 v10, 0x3fb8aa3b, v10
	v_mul_f32_e32 v11, 0x3fb8aa3b, v11
	v_exp_f32_e32 v10, v10
	v_exp_f32_e32 v11, v11
	v_sub_f32_e32 v10, 1.0, v10
	v_sub_f32_e32 v11, 1.0, v11
	v_max_f32_e32 v10, 0, v10
	v_max_f32_e32 v11, 0, v11
	v_sqrt_f32_e32 v10, v10
	v_sqrt_f32_e32 v11, v11
	s_waitcnt vmcnt(0)
	v_lshlrev_b32_e32 v24, 16, v20
	v_and_b32_e32 v25, 0xffff0000, v20
	v_pk_mul_f32 v[10:11], v[14:15], v[10:11]
	v_lshlrev_b32_e32 v20, 16, v21
	v_pk_mul_f32 v[14:15], v[10:11], v[24:25]
	v_add_f32_e32 v11, v16, v68
	v_mul_f32_e32 v11, 0xbfb8aa3b, v11
	v_exp_f32_e32 v11, v11
	v_add_f32_e32 v10, v12, v72
	v_mul_f32_e32 v10, 0xbfb8aa3b, v10
	v_exp_f32_e32 v10, v10
	v_add_f32_e32 v11, 1.0, v11
	v_rcp_f32_e32 v12, v11
	v_add_f32_e32 v11, v13, v73
	v_mul_f32_e32 v11, 0xbfb8aa3b, v11
	v_exp_f32_e32 v11, v11
	v_add_f32_e32 v10, 1.0, v10
	v_rcp_f32_e32 v10, v10
	v_add_f32_e32 v13, v17, v69
	v_add_f32_e32 v11, 1.0, v11
	v_rcp_f32_e32 v11, v11
	v_mul_f32_e32 v13, 0xbfb8aa3b, v13
	v_exp_f32_e32 v13, v13
	v_and_b32_e32 v21, 0xffff0000, v21
	v_pk_mul_f32 v[16:17], v[10:11], v[60:61]
	v_cvt_pk_bf16_f32 v14, v14, v15
	v_add_f32_e32 v10, v16, v16
	v_add_f32_e32 v11, v17, v17
	v_mul_f32_e32 v10, 0x3fb8aa3b, v10
	v_mul_f32_e32 v11, 0x3fb8aa3b, v11
	v_exp_f32_e32 v10, v10
	v_exp_f32_e32 v11, v11
	v_add_f32_e32 v13, 1.0, v13
	v_rcp_f32_e32 v13, v13
	v_sub_f32_e32 v10, 1.0, v10
	v_sub_f32_e32 v11, 1.0, v11
	v_max_f32_e32 v10, 0, v10
	v_max_f32_e32 v11, 0, v11
	v_sqrt_f32_e32 v10, v10
	v_sqrt_f32_e32 v11, v11
	s_nop 0
	v_pk_mul_f32 v[10:11], v[12:13], v[10:11]
	s_nop 0
	v_pk_mul_f32 v[12:13], v[10:11], v[20:21]
	v_cvt_pk_bf16_f32 v21, v16, v17
	v_mad_i64_i32 v[16:17], s[6:7], v18, s84, v[130:131]
	v_lshl_add_u64 v[16:17], v[16:17], 0, v[62:63]
	v_add_co_u32_e32 v16, vcc, s69, v16
	v_add_u32_e32 v10, 16, v18
	v_cvt_pk_bf16_f32 v20, v22, v23
	v_addc_co_u32_e32 v17, vcc, 0, v17, vcc
	v_cvt_pk_bf16_f32 v15, v12, v13
	global_store_dwordx2 v[16:17], v[20:21], off offset:2048
	global_store_dwordx2 v[16:17], v[14:15], off
	s_nop 0
	v_ashrrev_i32_e32 v11, 31, v10
	v_lshlrev_b64 v[12:13], 11, v[10:11]
	v_lshl_add_u64 v[12:13], s[14:15], 0, v[12:13]
	v_lshl_add_u64 v[12:13], v[12:13], 0, v[146:147]
	global_load_dwordx2 v[12:13], v[12:13], off offset:8
	v_add_f32_e32 v11, v2, v2
	v_mul_f32_e32 v11, 0x3fb8aa3b, v11
	v_exp_f32_e32 v11, v11
	v_cvt_pk_bf16_f32 v2, v2, v3
	v_sub_f32_e32 v11, 1.0, v11
	v_max_f32_e32 v11, 0, v11
	v_sqrt_f32_e32 v14, v11
	v_add_f32_e32 v11, v3, v3
	v_mul_f32_e32 v11, 0x3fb8aa3b, v11
	v_exp_f32_e32 v11, v11
	v_cvt_pk_bf16_f32 v3, v4, v5
	v_sub_f32_e32 v11, 1.0, v11
	v_max_f32_e32 v11, 0, v11
	v_sqrt_f32_e32 v15, v11
	v_add_f32_e32 v11, v4, v4
	v_mul_f32_e32 v11, 0x3fb8aa3b, v11
	v_exp_f32_e32 v11, v11
	v_pk_mul_f32 v[6:7], v[6:7], v[14:15]
	v_sub_f32_e32 v11, 1.0, v11
	v_max_f32_e32 v11, 0, v11
	v_sqrt_f32_e32 v14, v11
	v_add_f32_e32 v11, v5, v5
	v_mul_f32_e32 v11, 0x3fb8aa3b, v11
	v_exp_f32_e32 v11, v11
	v_mad_i64_i32 v[4:5], s[6:7], v10, s84, v[130:131]
	v_lshl_add_u64 v[4:5], v[4:5], 0, v[62:63]
	v_sub_f32_e32 v11, 1.0, v11
	v_max_f32_e32 v11, 0, v11
	v_sqrt_f32_e32 v15, v11
	v_add_co_u32_e32 v4, vcc, s69, v4
	v_pk_mul_f32 v[8:9], v[8:9], v[14:15]
	s_nop 0
	v_addc_co_u32_e32 v5, vcc, 0, v5, vcc
	global_store_dwordx2 v[4:5], v[2:3], off offset:2048
	s_andn2_b64 vcc, exec, s[4:5]
	s_waitcnt vmcnt(0)
	v_lshlrev_b32_e32 v16, 16, v12
	v_and_b32_e32 v17, 0xffff0000, v12
	v_lshlrev_b32_e32 v12, 16, v13
	v_and_b32_e32 v13, 0xffff0000, v13
	v_pk_mul_f32 v[6:7], v[6:7], v[16:17]
	v_pk_mul_f32 v[8:9], v[8:9], v[12:13]
	v_cvt_pk_bf16_f32 v2, v6, v7
	v_cvt_pk_bf16_f32 v3, v8, v9
	global_store_dwordx2 v[4:5], v[2:3], off
	s_cbranch_vccz .LBB0_1214
